# GEMM K-loops: removed per-block s_setprio flips and the redundant post-barrier lgkmcnt(0) wait (on top of 4/4 DMA rebalance + scan norm rewrite)
# speedup vs baseline: 1.0100x; 1.0034x over previous
; #define PG8_STAGE(bufoff, gbase, voff) do { _Pragma("unroll") for (int _i = 0; _i < 2; ++_i) \
;         __builtin_amdgcn_global_load_lds((const unsigned*)((const char*)(gbase) + (voff)[_i]), (PG8_LAS unsigned*)(lds + (bufoff) + ldsw + _i * 8192), 16, 0, 0); } while (0)
; #define PG8_LDA(dst, b, h) do { _Pragma("unroll") for (int m = 0; m < 4; ++m) _Pragma("unroll") for (int k = 0; k < 2; ++k) dst[m][k] = *(const PG8_LAS bf16x8*)(lds + PG8_SA(b, h) + aoff + m * 2048 + k * 1024); } while (0)
; #define PG8_LDB(dst, b, h) do { _Pragma("unroll") for (int n = 0; n < 2; ++n) _Pragma("unroll") for (int k = 0; k < 2; ++k) dst[n][k] = *(const PG8_LAS bf16x8*)(lds + PG8_SB(b, h) + boff + n * 2048 + k * 1024); } while (0)
; #define PG8_MMA(ai, bj, At, Bt) do { __builtin_amdgcn_s_setprio(1); _Pragma("unroll") for (int m = 0; m < 4; ++m) _Pragma("unroll") for (int n = 0; n < 2; ++n) _Pragma("unroll") for (int k = 0; k < 2; ++k) \
;         acc[ai][bj][m][n] = __builtin_amdgcn_mfma_f32_16x16x32_bf16(Bt[n][k], At[m][k], acc[ai][bj][m][n], 0, 0, 0); __builtin_amdgcn_s_setprio(0); } while (0)
; #define PG8_WAIT_V(n) asm volatile("s_waitcnt vmcnt(" #n ")" ::: "memory")
; #define PG8_WAIT_L(n) asm volatile("s_waitcnt lgkmcnt(" #n ")" ::: "memory")
; #define PG8_BAR __builtin_amdgcn_s_barrier()
; #define PG8_SCHED __builtin_amdgcn_sched_barrier(0)
; template <class Epi, class Sched, bool ALIGN_EPI = false, bool SP2 = false>
; __device__ __forceinline__ void gemm_phase(PG8_LAS unsigned char* lds, const Gemm g, const Sched& S, const Epi& E) {
;     ...
;             PG8_LDB(B0, 0, 0); PG8_LDB(B1, 0, 1); PG8_SCHED; PG8_LDA(At, 0, 0); PG8_STAGE(PG8_SA(1, 1), a1 + hstep, voffA);
;             PG8_WAIT_V(8); PG8_WAIT_L(0); PG8_BAR; PG8_MMA(0, 0, At, B0); PG8_MMA(0, 1, At, B1); PG8_BAR; PG8_SCHED;
;             PG8_LDA(At, 0, 1); PG8_STAGE(PG8_SB(0, 0), b2, voffB); PG8_STAGE(PG8_SB(0, 1), b2 + hstep, voffB); PG8_STAGE(PG8_SA(0, 0), a2, voffA);
.LBB0_180:
	s_add_u32 s36, s34, 0xfff00000
	s_addc_u32 s37, s35, -1
	v_lshl_add_u64 v[156:157], s[36:37], 0, v[138:139]
	s_mov_b32 m0, s45
	s_nop 0
	global_load_lds_dwordx4 v[156:157], off
	v_lshl_add_u64 v[156:157], s[36:37], 0, v[142:143]
	s_mov_b32 m0, s46
	s_nop 0
	global_load_lds_dwordx4 v[156:157], off
	s_add_u32 s36, s36, 0x80
	s_addc_u32 s37, s37, 0
	ds_read_b128 v[130:133], v170
	ds_read_b128 v[134:137], v170 offset:1024
	ds_read_b128 v[178:181], v170 offset:2048
	ds_read_b128 v[182:185], v170 offset:3072
	ds_read_b128 v[186:189], v171
	ds_read_b128 v[190:193], v171 offset:1024
	ds_read_b128 v[194:197], v171 offset:2048
	ds_read_b128 v[200:203], v171 offset:3072
	s_cmp_eq_u32 s56, 60
	s_cselect_b32 s39, s7, s37
	s_cselect_b32 s38, s25, s36
	s_cselect_b32 s37, s15, s55
	s_cselect_b32 s36, s31, s54
	v_lshl_add_u64 v[156:157], s[34:35], 0, v[148:149]
	s_add_i32 m0, s40, 0xc000
	ds_read_b128 v[204:207], v172
	ds_read_b128 v[208:211], v172 offset:1024
	ds_read_b128 v[212:215], v172 offset:2048
	ds_read_b128 v[216:219], v172 offset:3072
	ds_read_b128 v[220:223], v172 offset:4096
	ds_read_b128 v[224:227], v172 offset:5120
	ds_read_b128 v[228:231], v172 offset:6144
	ds_read_b128 v[232:235], v172 offset:7168
	global_load_lds_dwordx4 v[156:157], off
	v_lshl_add_u64 v[156:157], s[34:35], 0, v[150:151]
	s_add_i32 m0, s40, 0xe000
	s_nop 0
	global_load_lds_dwordx4 v[156:157], off
	s_waitcnt vmcnt(8)
	s_waitcnt lgkmcnt(0)
	s_barrier
	v_mfma_f32_16x16x32_bf16 v[126:129], v[130:133], v[204:207], v[126:129]
	v_mfma_f32_16x16x32_bf16 v[122:125], v[178:181], v[204:207], v[122:125]
	v_mfma_f32_16x16x32_bf16 v[110:113], v[130:133], v[212:215], v[110:113]
	v_mfma_f32_16x16x32_bf16 v[106:109], v[178:181], v[212:215], v[106:109]
	v_mfma_f32_16x16x32_bf16 v[94:97], v[130:133], v[220:223], v[94:97]
	v_mfma_f32_16x16x32_bf16 v[90:93], v[178:181], v[220:223], v[90:93]
	v_mfma_f32_16x16x32_bf16 v[78:81], v[130:133], v[228:231], v[78:81]
	v_mfma_f32_16x16x32_bf16 v[74:77], v[178:181], v[228:231], v[74:77]
	v_mfma_f32_16x16x32_bf16 v[126:129], v[134:137], v[208:211], v[126:129]
	v_mfma_f32_16x16x32_bf16 v[122:125], v[182:185], v[208:211], v[122:125]
	v_mfma_f32_16x16x32_bf16 v[110:113], v[134:137], v[216:219], v[110:113]
	v_mfma_f32_16x16x32_bf16 v[106:109], v[182:185], v[216:219], v[106:109]
	v_mfma_f32_16x16x32_bf16 v[94:97], v[134:137], v[224:227], v[94:97]
	v_mfma_f32_16x16x32_bf16 v[90:93], v[182:185], v[224:227], v[90:93]
	v_mfma_f32_16x16x32_bf16 v[78:81], v[134:137], v[232:235], v[78:81]
	v_mfma_f32_16x16x32_bf16 v[74:77], v[182:185], v[232:235], v[74:77]
	v_mfma_f32_16x16x32_bf16 v[118:121], v[186:189], v[204:207], v[118:121]
	v_mfma_f32_16x16x32_bf16 v[114:117], v[194:197], v[204:207], v[114:117]
	v_mfma_f32_16x16x32_bf16 v[102:105], v[186:189], v[212:215], v[102:105]
	v_mfma_f32_16x16x32_bf16 v[98:101], v[194:197], v[212:215], v[98:101]
	v_mfma_f32_16x16x32_bf16 v[86:89], v[186:189], v[220:223], v[86:89]
	v_mfma_f32_16x16x32_bf16 v[82:85], v[194:197], v[220:223], v[82:85]
	v_mfma_f32_16x16x32_bf16 v[70:73], v[186:189], v[228:231], v[70:73]
	v_mfma_f32_16x16x32_bf16 v[66:69], v[194:197], v[228:231], v[66:69]
	v_mfma_f32_16x16x32_bf16 v[118:121], v[190:193], v[208:211], v[118:121]
	v_mfma_f32_16x16x32_bf16 v[114:117], v[200:203], v[208:211], v[114:117]
	v_mfma_f32_16x16x32_bf16 v[102:105], v[190:193], v[216:219], v[102:105]
	v_mfma_f32_16x16x32_bf16 v[98:101], v[200:203], v[216:219], v[98:101]
	v_mfma_f32_16x16x32_bf16 v[86:89], v[190:193], v[224:227], v[86:89]
	v_mfma_f32_16x16x32_bf16 v[82:85], v[200:203], v[224:227], v[82:85]
	v_mfma_f32_16x16x32_bf16 v[70:73], v[190:193], v[232:235], v[70:73]
	v_mfma_f32_16x16x32_bf16 v[66:69], v[200:203], v[232:235], v[66:69]
	s_barrier
	s_add_i32 s57, s49, s33
	v_lshl_add_u64 v[156:157], s[36:37], 0, v[140:141]
	s_mov_b32 m0, s57
	ds_read_b128 v[204:207], v172 offset:16384
	ds_read_b128 v[208:211], v172 offset:17408
	ds_read_b128 v[212:215], v172 offset:18432
	ds_read_b128 v[216:219], v172 offset:19456
	ds_read_b128 v[220:223], v172 offset:20480
	ds_read_b128 v[224:227], v172 offset:21504
	ds_read_b128 v[228:231], v172 offset:22528
	ds_read_b128 v[232:235], v172 offset:23552
	global_load_lds_dwordx4 v[156:157], off
	s_add_i32 m0, s57, 0x2000
	s_add_u32 s58, s36, 0x100000
	v_lshl_add_u64 v[236:237], s[36:37], 0, v[144:145]
	s_addc_u32 s59, s37, 0
	s_add_i32 s57, s50, s33
	global_load_lds_dwordx4 v[236:237], off
	v_lshl_add_u64 v[238:239], s[58:59], 0, v[140:141]
	s_mov_b32 m0, s57
	v_lshl_add_u64 v[240:241], s[38:39], 0, v[142:143]
	global_load_lds_dwordx4 v[238:239], off
	v_lshl_add_u64 v[238:239], s[58:59], 0, v[144:145]
	s_add_i32 m0, s57, 0x2000
	s_nop 0
	global_load_lds_dwordx4 v[238:239], off
	v_lshl_add_u64 v[238:239], s[38:39], 0, v[138:139]
	s_waitcnt vmcnt(6)
	s_waitcnt lgkmcnt(0)
	s_barrier
; #define PG8_STAGE(bufoff, gbase, voff) do { _Pragma("unroll") for (int _i = 0; _i < 2; ++_i) \
;         __builtin_amdgcn_global_load_lds((const unsigned*)((const char*)(gbase) + (voff)[_i]), (PG8_LAS unsigned*)(lds + (bufoff) + ldsw + _i * 8192), 16, 0, 0); } while (0)
; #define PG8_LDA(dst, b, h) do { _Pragma("unroll") for (int m = 0; m < 4; ++m) _Pragma("unroll") for (int k = 0; k < 2; ++k) dst[m][k] = *(const PG8_LAS bf16x8*)(lds + PG8_SA(b, h) + aoff + m * 2048 + k * 1024); } while (0)
; #define PG8_LDB(dst, b, h) do { _Pragma("unroll") for (int n = 0; n < 2; ++n) _Pragma("unroll") for (int k = 0; k < 2; ++k) dst[n][k] = *(const PG8_LAS bf16x8*)(lds + PG8_SB(b, h) + boff + n * 2048 + k * 1024); } while (0)
; #define PG8_MMA(ai, bj, At, Bt) do { __builtin_amdgcn_s_setprio(1); _Pragma("unroll") for (int m = 0; m < 4; ++m) _Pragma("unroll") for (int n = 0; n < 2; ++n) _Pragma("unroll") for (int k = 0; k < 2; ++k) \
;         acc[ai][bj][m][n] = __builtin_amdgcn_mfma_f32_16x16x32_bf16(Bt[n][k], At[m][k], acc[ai][bj][m][n], 0, 0, 0); __builtin_amdgcn_s_setprio(0); } while (0)
; #define PG8_WAIT_V(n) asm volatile("s_waitcnt vmcnt(" #n ")" ::: "memory")
; #define PG8_WAIT_L(n) asm volatile("s_waitcnt lgkmcnt(" #n ")" ::: "memory")
; #define PG8_BAR __builtin_amdgcn_s_barrier()
; #define PG8_SCHED __builtin_amdgcn_sched_barrier(0)
; template <class Epi, class Sched, bool ALIGN_EPI = false, bool SP2 = false>
; __device__ __forceinline__ void gemm_phase(PG8_LAS unsigned char* lds, const Gemm g, const Sched& S, const Epi& E) {
;     ...
;             PG8_WAIT_V(8); PG8_WAIT_L(0); PG8_BAR; PG8_MMA(1, 0, At, B0); PG8_MMA(1, 1, At, B1); PG8_BAR; PG8_SCHED;
;             PG8_LDB(B0, 1, 0); PG8_LDB(B1, 1, 1); PG8_SCHED; PG8_LDA(At, 1, 0); PG8_STAGE(PG8_SA(0, 1), a2 + hstep, voffA);
	v_mfma_f32_16x16x32_bf16 v[62:65], v[130:133], v[204:207], v[62:65]
	v_mfma_f32_16x16x32_bf16 v[58:61], v[178:181], v[204:207], v[58:61]
	v_mfma_f32_16x16x32_bf16 v[46:49], v[130:133], v[212:215], v[46:49]
	v_mfma_f32_16x16x32_bf16 v[42:45], v[178:181], v[212:215], v[42:45]
	v_mfma_f32_16x16x32_bf16 v[30:33], v[130:133], v[220:223], v[30:33]
	v_mfma_f32_16x16x32_bf16 v[26:29], v[178:181], v[220:223], v[26:29]
	v_mfma_f32_16x16x32_bf16 v[14:17], v[130:133], v[228:231], v[14:17]
	v_mfma_f32_16x16x32_bf16 v[10:13], v[178:181], v[228:231], v[10:13]
	v_mfma_f32_16x16x32_bf16 v[62:65], v[134:137], v[208:211], v[62:65]
	v_mfma_f32_16x16x32_bf16 v[58:61], v[182:185], v[208:211], v[58:61]
	v_mfma_f32_16x16x32_bf16 v[46:49], v[134:137], v[216:219], v[46:49]
	v_mfma_f32_16x16x32_bf16 v[42:45], v[182:185], v[216:219], v[42:45]
	v_mfma_f32_16x16x32_bf16 v[30:33], v[134:137], v[224:227], v[30:33]
	v_mfma_f32_16x16x32_bf16 v[26:29], v[182:185], v[224:227], v[26:29]
	v_mfma_f32_16x16x32_bf16 v[14:17], v[134:137], v[232:235], v[14:17]
	v_mfma_f32_16x16x32_bf16 v[10:13], v[182:185], v[232:235], v[10:13]
	v_mfma_f32_16x16x32_bf16 v[54:57], v[186:189], v[204:207], v[54:57]
	v_mfma_f32_16x16x32_bf16 v[50:53], v[194:197], v[204:207], v[50:53]
	v_mfma_f32_16x16x32_bf16 v[38:41], v[186:189], v[212:215], v[38:41]
	v_mfma_f32_16x16x32_bf16 v[34:37], v[194:197], v[212:215], v[34:37]
	v_mfma_f32_16x16x32_bf16 v[22:25], v[186:189], v[220:223], v[22:25]
	v_mfma_f32_16x16x32_bf16 v[18:21], v[194:197], v[220:223], v[18:21]
	v_mfma_f32_16x16x32_bf16 v[6:9], v[186:189], v[228:231], v[6:9]
	v_mfma_f32_16x16x32_bf16 v[2:5], v[194:197], v[228:231], v[2:5]
	v_mfma_f32_16x16x32_bf16 v[54:57], v[190:193], v[208:211], v[54:57]
	v_mfma_f32_16x16x32_bf16 v[50:53], v[200:203], v[208:211], v[50:53]
	v_mfma_f32_16x16x32_bf16 v[38:41], v[190:193], v[216:219], v[38:41]
	v_mfma_f32_16x16x32_bf16 v[34:37], v[200:203], v[216:219], v[34:37]
	v_mfma_f32_16x16x32_bf16 v[22:25], v[190:193], v[224:227], v[22:25]
	v_mfma_f32_16x16x32_bf16 v[18:21], v[200:203], v[224:227], v[18:21]
	v_mfma_f32_16x16x32_bf16 v[6:9], v[190:193], v[232:235], v[6:9]
	v_mfma_f32_16x16x32_bf16 v[2:5], v[200:203], v[232:235], v[2:5]
	s_barrier
	s_mov_b32 m0, s40
	s_nop 0
	global_load_lds_dwordx4 v[238:239], off
	s_mov_b32 m0, s41
	s_nop 0
	global_load_lds_dwordx4 v[240:241], off
	s_add_i32 s57, 0, 0x18000
	v_add_u32_e32 v146, s57, v159
	s_add_i32 s58, 0, 0x1c000
	ds_read_b128 v[130:133], v146
	ds_read_b128 v[134:137], v146 offset:1024
	ds_read_b128 v[178:181], v146 offset:2048
	ds_read_b128 v[182:185], v146 offset:3072
	v_add_u32_e32 v146, s58, v159
	ds_read_b128 v[186:189], v146
	ds_read_b128 v[190:193], v146 offset:1024
	ds_read_b128 v[194:197], v146 offset:2048
	ds_read_b128 v[200:203], v146 offset:3072
	s_add_u32 s38, s38, 0x100000
	s_addc_u32 s39, s39, 0
	s_mov_b32 m0, s42
	v_lshl_add_u64 v[242:243], s[38:39], 0, v[138:139]
	ds_read_b128 v[204:207], v172 offset:32768
	ds_read_b128 v[208:211], v172 offset:33792
	ds_read_b128 v[212:215], v172 offset:34816
	ds_read_b128 v[216:219], v172 offset:35840
	ds_read_b128 v[220:223], v172 offset:36864
	ds_read_b128 v[224:227], v172 offset:37888
	ds_read_b128 v[228:231], v172 offset:38912
	ds_read_b128 v[232:235], v172 offset:39936
	global_load_lds_dwordx4 v[242:243], off
	v_lshl_add_u64 v[242:243], s[38:39], 0, v[142:143]
	s_mov_b32 m0, s43
	s_nop 0
	global_load_lds_dwordx4 v[242:243], off
	s_waitcnt vmcnt(8)
	s_waitcnt lgkmcnt(0)
	s_barrier
; #define PG8_STAGE(bufoff, gbase, voff) do { _Pragma("unroll") for (int _i = 0; _i < 2; ++_i) \
;         __builtin_amdgcn_global_load_lds((const unsigned*)((const char*)(gbase) + (voff)[_i]), (PG8_LAS unsigned*)(lds + (bufoff) + ldsw + _i * 8192), 16, 0, 0); } while (0)
; #define PG8_LDA(dst, b, h) do { _Pragma("unroll") for (int m = 0; m < 4; ++m) _Pragma("unroll") for (int k = 0; k < 2; ++k) dst[m][k] = *(const PG8_LAS bf16x8*)(lds + PG8_SA(b, h) + aoff + m * 2048 + k * 1024); } while (0)
; #define PG8_MMA(ai, bj, At, Bt) do { __builtin_amdgcn_s_setprio(1); _Pragma("unroll") for (int m = 0; m < 4; ++m) _Pragma("unroll") for (int n = 0; n < 2; ++n) _Pragma("unroll") for (int k = 0; k < 2; ++k) \
;         acc[ai][bj][m][n] = __builtin_amdgcn_mfma_f32_16x16x32_bf16(Bt[n][k], At[m][k], acc[ai][bj][m][n], 0, 0, 0); __builtin_amdgcn_s_setprio(0); } while (0)
; #define PG8_WAIT_V(n) asm volatile("s_waitcnt vmcnt(" #n ")" ::: "memory")
; #define PG8_WAIT_L(n) asm volatile("s_waitcnt lgkmcnt(" #n ")" ::: "memory")
; #define PG8_BAR __builtin_amdgcn_s_barrier()
; #define PG8_SCHED __builtin_amdgcn_sched_barrier(0)
; template <class Epi, class Sched, bool ALIGN_EPI = false, bool SP2 = false>
; __device__ __forceinline__ void gemm_phase(PG8_LAS unsigned char* lds, const Gemm g, const Sched& S, const Epi& E) {
;     ...
;             PG8_WAIT_V(8); PG8_WAIT_L(0); PG8_BAR; PG8_MMA(0, 0, At, B0); PG8_MMA(0, 1, At, B1); PG8_BAR; PG8_SCHED;
;             PG8_LDA(At, 1, 1); PG8_STAGE(PG8_SB(1, 0), b3, voffB); PG8_STAGE(PG8_SB(1, 1), b3 + hstep, voffB); PG8_STAGE(PG8_SA(1, 0), a3, voffA);
;             PG8_WAIT_V(8); PG8_WAIT_L(0); PG8_BAR; PG8_MMA(1, 0, At, B0); PG8_MMA(1, 1, At, B1); PG8_BAR; PG8_SCHED;
	v_mfma_f32_16x16x32_bf16 v[126:129], v[130:133], v[204:207], v[126:129]
	v_mfma_f32_16x16x32_bf16 v[122:125], v[178:181], v[204:207], v[122:125]
	v_mfma_f32_16x16x32_bf16 v[110:113], v[130:133], v[212:215], v[110:113]
	v_mfma_f32_16x16x32_bf16 v[106:109], v[178:181], v[212:215], v[106:109]
	v_mfma_f32_16x16x32_bf16 v[94:97], v[130:133], v[220:223], v[94:97]
	v_mfma_f32_16x16x32_bf16 v[90:93], v[178:181], v[220:223], v[90:93]
	v_mfma_f32_16x16x32_bf16 v[78:81], v[130:133], v[228:231], v[78:81]
	v_mfma_f32_16x16x32_bf16 v[74:77], v[178:181], v[228:231], v[74:77]
	v_mfma_f32_16x16x32_bf16 v[126:129], v[134:137], v[208:211], v[126:129]
	v_mfma_f32_16x16x32_bf16 v[122:125], v[182:185], v[208:211], v[122:125]
	v_mfma_f32_16x16x32_bf16 v[110:113], v[134:137], v[216:219], v[110:113]
	v_mfma_f32_16x16x32_bf16 v[106:109], v[182:185], v[216:219], v[106:109]
	v_mfma_f32_16x16x32_bf16 v[94:97], v[134:137], v[224:227], v[94:97]
	v_mfma_f32_16x16x32_bf16 v[90:93], v[182:185], v[224:227], v[90:93]
	v_mfma_f32_16x16x32_bf16 v[78:81], v[134:137], v[232:235], v[78:81]
	v_mfma_f32_16x16x32_bf16 v[74:77], v[182:185], v[232:235], v[74:77]
	v_mfma_f32_16x16x32_bf16 v[118:121], v[186:189], v[204:207], v[118:121]
	v_mfma_f32_16x16x32_bf16 v[114:117], v[194:197], v[204:207], v[114:117]
	v_mfma_f32_16x16x32_bf16 v[102:105], v[186:189], v[212:215], v[102:105]
	v_mfma_f32_16x16x32_bf16 v[98:101], v[194:197], v[212:215], v[98:101]
	v_mfma_f32_16x16x32_bf16 v[86:89], v[186:189], v[220:223], v[86:89]
	v_mfma_f32_16x16x32_bf16 v[82:85], v[194:197], v[220:223], v[82:85]
	v_mfma_f32_16x16x32_bf16 v[70:73], v[186:189], v[228:231], v[70:73]
	v_mfma_f32_16x16x32_bf16 v[66:69], v[194:197], v[228:231], v[66:69]
	v_mfma_f32_16x16x32_bf16 v[118:121], v[190:193], v[208:211], v[118:121]
	v_mfma_f32_16x16x32_bf16 v[114:117], v[200:203], v[208:211], v[114:117]
	v_mfma_f32_16x16x32_bf16 v[102:105], v[190:193], v[216:219], v[102:105]
	v_mfma_f32_16x16x32_bf16 v[98:101], v[200:203], v[216:219], v[98:101]
	v_mfma_f32_16x16x32_bf16 v[86:89], v[190:193], v[224:227], v[86:89]
	v_mfma_f32_16x16x32_bf16 v[82:85], v[200:203], v[224:227], v[82:85]
	v_mfma_f32_16x16x32_bf16 v[70:73], v[190:193], v[232:235], v[70:73]
	v_mfma_f32_16x16x32_bf16 v[66:69], v[200:203], v[232:235], v[66:69]
	s_barrier
	s_add_i32 s38, s57, s33
	v_lshl_add_u64 v[156:157], v[156:157], 0, s[10:11]
	s_mov_b32 m0, s38
	ds_read_b128 v[204:207], v172 offset:49152
	ds_read_b128 v[208:211], v172 offset:50176
	ds_read_b128 v[212:215], v172 offset:51200
	ds_read_b128 v[216:219], v172 offset:52224
	ds_read_b128 v[220:223], v172 offset:53248
	ds_read_b128 v[224:227], v172 offset:54272
	ds_read_b128 v[228:231], v172 offset:55296
	ds_read_b128 v[232:235], v172 offset:56320
	global_load_lds_dwordx4 v[156:157], off
	s_add_i32 m0, s38, 0x2000
	s_add_u32 s36, s36, 0x100080
	v_lshl_add_u64 v[156:157], v[236:237], 0, s[10:11]
	s_addc_u32 s37, s37, 0
	s_add_i32 s38, s58, s33
	global_load_lds_dwordx4 v[156:157], off
	v_lshl_add_u64 v[156:157], s[36:37], 0, v[140:141]
	s_mov_b32 m0, s38
	s_nop 0
	global_load_lds_dwordx4 v[156:157], off
	v_lshl_add_u64 v[156:157], s[36:37], 0, v[144:145]
	s_add_i32 m0, s38, 0x2000
	s_nop 0
	global_load_lds_dwordx4 v[156:157], off
	s_waitcnt vmcnt(6)
	s_waitcnt lgkmcnt(0)
	s_barrier
	v_mfma_f32_16x16x32_bf16 v[62:65], v[130:133], v[204:207], v[62:65]
	v_mfma_f32_16x16x32_bf16 v[58:61], v[178:181], v[204:207], v[58:61]
	v_mfma_f32_16x16x32_bf16 v[46:49], v[130:133], v[212:215], v[46:49]
	v_mfma_f32_16x16x32_bf16 v[42:45], v[178:181], v[212:215], v[42:45]
	v_mfma_f32_16x16x32_bf16 v[30:33], v[130:133], v[220:223], v[30:33]
	v_mfma_f32_16x16x32_bf16 v[26:29], v[178:181], v[220:223], v[26:29]
	v_mfma_f32_16x16x32_bf16 v[14:17], v[130:133], v[228:231], v[14:17]
	v_mfma_f32_16x16x32_bf16 v[10:13], v[178:181], v[228:231], v[10:13]
	v_mfma_f32_16x16x32_bf16 v[62:65], v[134:137], v[208:211], v[62:65]
	v_mfma_f32_16x16x32_bf16 v[58:61], v[182:185], v[208:211], v[58:61]
	v_mfma_f32_16x16x32_bf16 v[46:49], v[134:137], v[216:219], v[46:49]
	v_mfma_f32_16x16x32_bf16 v[42:45], v[182:185], v[216:219], v[42:45]
	v_mfma_f32_16x16x32_bf16 v[30:33], v[134:137], v[224:227], v[30:33]
	v_mfma_f32_16x16x32_bf16 v[26:29], v[182:185], v[224:227], v[26:29]
	v_mfma_f32_16x16x32_bf16 v[14:17], v[134:137], v[232:235], v[14:17]
	v_mfma_f32_16x16x32_bf16 v[10:13], v[182:185], v[232:235], v[10:13]
	v_mfma_f32_16x16x32_bf16 v[54:57], v[186:189], v[204:207], v[54:57]
	v_mfma_f32_16x16x32_bf16 v[50:53], v[194:197], v[204:207], v[50:53]
	v_mfma_f32_16x16x32_bf16 v[38:41], v[186:189], v[212:215], v[38:41]
	v_mfma_f32_16x16x32_bf16 v[34:37], v[194:197], v[212:215], v[34:37]
	v_mfma_f32_16x16x32_bf16 v[22:25], v[186:189], v[220:223], v[22:25]
	v_mfma_f32_16x16x32_bf16 v[18:21], v[194:197], v[220:223], v[18:21]
	v_mfma_f32_16x16x32_bf16 v[6:9], v[186:189], v[228:231], v[6:9]
	v_mfma_f32_16x16x32_bf16 v[2:5], v[194:197], v[228:231], v[2:5]
	v_mfma_f32_16x16x32_bf16 v[54:57], v[190:193], v[208:211], v[54:57]
	v_mfma_f32_16x16x32_bf16 v[50:53], v[200:203], v[208:211], v[50:53]
	v_mfma_f32_16x16x32_bf16 v[38:41], v[190:193], v[216:219], v[38:41]
	v_mfma_f32_16x16x32_bf16 v[34:37], v[200:203], v[216:219], v[34:37]
	v_mfma_f32_16x16x32_bf16 v[22:25], v[190:193], v[224:227], v[22:25]
	v_mfma_f32_16x16x32_bf16 v[18:21], v[200:203], v[224:227], v[18:21]
	v_mfma_f32_16x16x32_bf16 v[6:9], v[190:193], v[232:235], v[6:9]
	v_mfma_f32_16x16x32_bf16 v[2:5], v[200:203], v[232:235], v[2:5]
	s_barrier
	s_add_i32 s56, s56, 2
	s_add_u32 s34, s34, 0x100
	s_addc_u32 s35, s35, 0
	s_add_u32 s54, s54, 0x100
	s_addc_u32 s55, s55, 0
	s_cmp_gt_u32 s56, 61
	s_cbranch_scc0 .LBB0_180
	s_and_b64 vcc, exec, s[12:13]
	s_cbranch_vccz .LBB0_183
	s_barrier

; #define PG8_STAGE(bufoff, gbase, voff) do { _Pragma("unroll") for (int _i = 0; _i < 2; ++_i) \
;         __builtin_amdgcn_global_load_lds((const unsigned*)((const char*)(gbase) + (voff)[_i]), (PG8_LAS unsigned*)(lds + (bufoff) + ldsw + _i * 8192), 16, 0, 0); } while (0)
; #define PG8_LDA(dst, b, h) do { _Pragma("unroll") for (int m = 0; m < 4; ++m) _Pragma("unroll") for (int k = 0; k < 2; ++k) dst[m][k] = *(const PG8_LAS bf16x8*)(lds + PG8_SA(b, h) + aoff + m * 2048 + k * 1024); } while (0)
; #define PG8_LDB(dst, b, h) do { _Pragma("unroll") for (int n = 0; n < 2; ++n) _Pragma("unroll") for (int k = 0; k < 2; ++k) dst[n][k] = *(const PG8_LAS bf16x8*)(lds + PG8_SB(b, h) + boff + n * 2048 + k * 1024); } while (0)
; #define PG8_MMA(ai, bj, At, Bt) do { __builtin_amdgcn_s_setprio(1); _Pragma("unroll") for (int m = 0; m < 4; ++m) _Pragma("unroll") for (int n = 0; n < 2; ++n) _Pragma("unroll") for (int k = 0; k < 2; ++k) \
;         acc[ai][bj][m][n] = __builtin_amdgcn_mfma_f32_16x16x32_bf16(Bt[n][k], At[m][k], acc[ai][bj][m][n], 0, 0, 0); __builtin_amdgcn_s_setprio(0); } while (0)
; #define PG8_WAIT_V(n) asm volatile("s_waitcnt vmcnt(" #n ")" ::: "memory")
; #define PG8_WAIT_L(n) asm volatile("s_waitcnt lgkmcnt(" #n ")" ::: "memory")
; template <class Epi, class Sched, bool ALIGN_EPI = false, bool SP2 = false>
; __device__ __forceinline__ void gemm_phase(PG8_LAS unsigned char* lds, const Gemm g, const Sched& S, const Epi& E) {
;     ...
;             const bool last = (t == nt - 2);
;             const char* a1 = cA + (size_t)(t + 1) * kstep;
;             const char* a2 = last ? nA : cA + (size_t)(t + 2) * kstep; const char* b2 = last ? nB : cB + (size_t)(t + 2) * kstep;
;             const char* a3 = a2 + kstep; const char* b3 = b2 + kstep;
;             if (last && has_next) S.a_ready(nxt);
;             if constexpr (SP2) {
;             PG8_LDB(B0, 0, 0); PG8_LDB(B1, 0, 1); PG8_SCHED; PG8_LDA(At, 0, 0); PG8_STAGE(PG8_SA(1, 1), a1 + hstep, voffA);
;             PG8_WAIT_V(8); PG8_WAIT_L(0); PG8_BAR; PG8_MMA(0, 0, At, B0); PG8_MMA(0, 1, At, B1); PG8_BAR; PG8_SCHED;
;             PG8_LDA(At, 0, 1); PG8_STAGE(PG8_SB(0, 0), b2, voffB); PG8_STAGE(PG8_SB(0, 1), b2 + hstep, voffB); PG8_STAGE(PG8_SA(0, 0), a2, voffA);
;             PG8_WAIT_V(8); PG8_WAIT_L(0); PG8_BAR; PG8_MMA(1, 0, At, B0); PG8_MMA(1, 1, At, B1); PG8_BAR; PG8_SCHED;
.LBB0_857:
	s_add_u32 s34, s30, 0xfff80000
	s_addc_u32 s35, s31, -1
	v_lshl_add_u64 v[196:197], s[34:35], 0, v[150:151]
	s_mov_b32 m0, s43
	s_nop 0
	global_load_lds_dwordx4 v[196:197], off
	v_lshl_add_u64 v[196:197], s[34:35], 0, v[154:155]
	s_mov_b32 m0, s44
	s_nop 0
	global_load_lds_dwordx4 v[196:197], off
	s_add_u32 s34, s34, 0x80
	s_addc_u32 s35, s35, 0
	ds_read_b128 v[130:133], v180
	ds_read_b128 v[134:137], v180 offset:1024
	ds_read_b128 v[138:141], v180 offset:2048
	ds_read_b128 v[142:145], v180 offset:3072
	ds_read_b128 v[146:149], v181
	ds_read_b128 v[166:169], v181 offset:1024
	ds_read_b128 v[170:173], v181 offset:2048
	ds_read_b128 v[174:177], v181 offset:3072
	s_cmp_eq_u32 s56, 28
	s_cselect_b32 s37, s15, s35
	s_cselect_b32 s36, s50, s34
	s_cselect_b32 s35, s13, s53
	s_cselect_b32 s34, s51, s52
	v_lshl_add_u64 v[196:197], s[30:31], 0, v[158:159]
	s_add_i32 m0, s29, 0xc000
	ds_read_b128 v[184:187], v182
	ds_read_b128 v[188:191], v182 offset:1024
	ds_read_b128 v[192:195], v182 offset:2048
	ds_read_b128 v[200:203], v182 offset:3072
	ds_read_b128 v[204:207], v182 offset:4096
	ds_read_b128 v[208:211], v182 offset:5120
	ds_read_b128 v[212:215], v182 offset:6144
	ds_read_b128 v[216:219], v182 offset:7168
	global_load_lds_dwordx4 v[196:197], off
	v_lshl_add_u64 v[196:197], s[30:31], 0, v[160:161]
	s_add_i32 m0, s29, 0xe000
	s_nop 0
	global_load_lds_dwordx4 v[196:197], off
	s_waitcnt vmcnt(8)
	s_waitcnt lgkmcnt(0)
	s_barrier
	v_mfma_f32_16x16x32_bf16 v[126:129], v[130:133], v[184:187], v[126:129]
	v_mfma_f32_16x16x32_bf16 v[122:125], v[138:141], v[184:187], v[122:125]
	v_mfma_f32_16x16x32_bf16 v[110:113], v[130:133], v[192:195], v[110:113]
	v_mfma_f32_16x16x32_bf16 v[106:109], v[138:141], v[192:195], v[106:109]
	v_mfma_f32_16x16x32_bf16 v[94:97], v[130:133], v[204:207], v[94:97]
	v_mfma_f32_16x16x32_bf16 v[90:93], v[138:141], v[204:207], v[90:93]
	v_mfma_f32_16x16x32_bf16 v[78:81], v[130:133], v[212:215], v[78:81]
	v_mfma_f32_16x16x32_bf16 v[74:77], v[138:141], v[212:215], v[74:77]
	v_mfma_f32_16x16x32_bf16 v[126:129], v[134:137], v[188:191], v[126:129]
	v_mfma_f32_16x16x32_bf16 v[122:125], v[142:145], v[188:191], v[122:125]
	v_mfma_f32_16x16x32_bf16 v[110:113], v[134:137], v[200:203], v[110:113]
	v_mfma_f32_16x16x32_bf16 v[106:109], v[142:145], v[200:203], v[106:109]
	v_mfma_f32_16x16x32_bf16 v[94:97], v[134:137], v[208:211], v[94:97]
	v_mfma_f32_16x16x32_bf16 v[90:93], v[142:145], v[208:211], v[90:93]
	v_mfma_f32_16x16x32_bf16 v[78:81], v[134:137], v[216:219], v[78:81]
	v_mfma_f32_16x16x32_bf16 v[74:77], v[142:145], v[216:219], v[74:77]
	v_mfma_f32_16x16x32_bf16 v[118:121], v[146:149], v[184:187], v[118:121]
	v_mfma_f32_16x16x32_bf16 v[114:117], v[170:173], v[184:187], v[114:117]
	v_mfma_f32_16x16x32_bf16 v[102:105], v[146:149], v[192:195], v[102:105]
	v_mfma_f32_16x16x32_bf16 v[98:101], v[170:173], v[192:195], v[98:101]
	v_mfma_f32_16x16x32_bf16 v[86:89], v[146:149], v[204:207], v[86:89]
	v_mfma_f32_16x16x32_bf16 v[82:85], v[170:173], v[204:207], v[82:85]
	v_mfma_f32_16x16x32_bf16 v[70:73], v[146:149], v[212:215], v[70:73]
	v_mfma_f32_16x16x32_bf16 v[66:69], v[170:173], v[212:215], v[66:69]
	v_mfma_f32_16x16x32_bf16 v[118:121], v[166:169], v[188:191], v[118:121]
	v_mfma_f32_16x16x32_bf16 v[114:117], v[174:177], v[188:191], v[114:117]
	v_mfma_f32_16x16x32_bf16 v[102:105], v[166:169], v[200:203], v[102:105]
	v_mfma_f32_16x16x32_bf16 v[98:101], v[174:177], v[200:203], v[98:101]
	v_mfma_f32_16x16x32_bf16 v[86:89], v[166:169], v[208:211], v[86:89]
	v_mfma_f32_16x16x32_bf16 v[82:85], v[174:177], v[208:211], v[82:85]
	v_mfma_f32_16x16x32_bf16 v[70:73], v[166:169], v[216:219], v[70:73]
	v_mfma_f32_16x16x32_bf16 v[66:69], v[174:177], v[216:219], v[66:69]
	s_barrier
	s_add_i32 s57, s46, s38
	v_lshl_add_u64 v[196:197], s[34:35], 0, v[152:153]
	s_mov_b32 m0, s57
	ds_read_b128 v[184:187], v182 offset:16384
	ds_read_b128 v[188:191], v182 offset:17408
	ds_read_b128 v[192:195], v182 offset:18432
	ds_read_b128 v[200:203], v182 offset:19456
	ds_read_b128 v[204:207], v182 offset:20480
	ds_read_b128 v[208:211], v182 offset:21504
	ds_read_b128 v[212:215], v182 offset:22528
	ds_read_b128 v[216:219], v182 offset:23552
	global_load_lds_dwordx4 v[196:197], off
	s_add_i32 m0, s57, 0x2000
	s_add_u32 s58, s34, 0x80000
	v_lshl_add_u64 v[220:221], s[34:35], 0, v[156:157]
	s_addc_u32 s59, s35, 0
	s_add_i32 s57, s47, s38
	global_load_lds_dwordx4 v[220:221], off
	v_lshl_add_u64 v[222:223], s[58:59], 0, v[152:153]
	s_mov_b32 m0, s57
	v_lshl_add_u64 v[224:225], s[36:37], 0, v[154:155]
	global_load_lds_dwordx4 v[222:223], off
	v_lshl_add_u64 v[222:223], s[58:59], 0, v[156:157]
	s_add_i32 m0, s57, 0x2000
	s_nop 0
	global_load_lds_dwordx4 v[222:223], off
	v_lshl_add_u64 v[222:223], s[36:37], 0, v[150:151]
	s_waitcnt vmcnt(6)
	s_waitcnt lgkmcnt(0)
	s_barrier
; #define PG8_STAGE(bufoff, gbase, voff) do { _Pragma("unroll") for (int _i = 0; _i < 2; ++_i) \
;         __builtin_amdgcn_global_load_lds((const unsigned*)((const char*)(gbase) + (voff)[_i]), (PG8_LAS unsigned*)(lds + (bufoff) + ldsw + _i * 8192), 16, 0, 0); } while (0)
; #define PG8_LDA(dst, b, h) do { _Pragma("unroll") for (int m = 0; m < 4; ++m) _Pragma("unroll") for (int k = 0; k < 2; ++k) dst[m][k] = *(const PG8_LAS bf16x8*)(lds + PG8_SA(b, h) + aoff + m * 2048 + k * 1024); } while (0)
; #define PG8_LDB(dst, b, h) do { _Pragma("unroll") for (int n = 0; n < 2; ++n) _Pragma("unroll") for (int k = 0; k < 2; ++k) dst[n][k] = *(const PG8_LAS bf16x8*)(lds + PG8_SB(b, h) + boff + n * 2048 + k * 1024); } while (0)
; #define PG8_MMA(ai, bj, At, Bt) do { __builtin_amdgcn_s_setprio(1); _Pragma("unroll") for (int m = 0; m < 4; ++m) _Pragma("unroll") for (int n = 0; n < 2; ++n) _Pragma("unroll") for (int k = 0; k < 2; ++k) \
;         acc[ai][bj][m][n] = __builtin_amdgcn_mfma_f32_16x16x32_bf16(Bt[n][k], At[m][k], acc[ai][bj][m][n], 0, 0, 0); __builtin_amdgcn_s_setprio(0); } while (0)
; #define PG8_WAIT_V(n) asm volatile("s_waitcnt vmcnt(" #n ")" ::: "memory")
; #define PG8_WAIT_L(n) asm volatile("s_waitcnt lgkmcnt(" #n ")" ::: "memory")
; #define PG8_BAR __builtin_amdgcn_s_barrier()
; #define PG8_SCHED __builtin_amdgcn_sched_barrier(0)
; template <class Epi, class Sched, bool ALIGN_EPI = false, bool SP2 = false>
; __device__ __forceinline__ void gemm_phase(PG8_LAS unsigned char* lds, const Gemm g, const Sched& S, const Epi& E) {
;     ...
;             PG8_WAIT_V(8); PG8_WAIT_L(0); PG8_BAR; PG8_MMA(1, 0, At, B0); PG8_MMA(1, 1, At, B1); PG8_BAR; PG8_SCHED;
;             PG8_LDB(B0, 1, 0); PG8_LDB(B1, 1, 1); PG8_SCHED; PG8_LDA(At, 1, 0); PG8_STAGE(PG8_SA(0, 1), a2 + hstep, voffA);
;             PG8_WAIT_V(8); PG8_WAIT_L(0); PG8_BAR; PG8_MMA(0, 0, At, B0); PG8_MMA(0, 1, At, B1); PG8_BAR; PG8_SCHED;
	v_mfma_f32_16x16x32_bf16 v[62:65], v[130:133], v[184:187], v[62:65]
	v_mfma_f32_16x16x32_bf16 v[58:61], v[138:141], v[184:187], v[58:61]
	v_mfma_f32_16x16x32_bf16 v[46:49], v[130:133], v[192:195], v[46:49]
	v_mfma_f32_16x16x32_bf16 v[42:45], v[138:141], v[192:195], v[42:45]
	v_mfma_f32_16x16x32_bf16 v[30:33], v[130:133], v[204:207], v[30:33]
	v_mfma_f32_16x16x32_bf16 v[26:29], v[138:141], v[204:207], v[26:29]
	v_mfma_f32_16x16x32_bf16 v[14:17], v[130:133], v[212:215], v[14:17]
	v_mfma_f32_16x16x32_bf16 v[10:13], v[138:141], v[212:215], v[10:13]
	v_mfma_f32_16x16x32_bf16 v[62:65], v[134:137], v[188:191], v[62:65]
	v_mfma_f32_16x16x32_bf16 v[58:61], v[142:145], v[188:191], v[58:61]
	v_mfma_f32_16x16x32_bf16 v[46:49], v[134:137], v[200:203], v[46:49]
	v_mfma_f32_16x16x32_bf16 v[42:45], v[142:145], v[200:203], v[42:45]
	v_mfma_f32_16x16x32_bf16 v[30:33], v[134:137], v[208:211], v[30:33]
	v_mfma_f32_16x16x32_bf16 v[26:29], v[142:145], v[208:211], v[26:29]
	v_mfma_f32_16x16x32_bf16 v[14:17], v[134:137], v[216:219], v[14:17]
	v_mfma_f32_16x16x32_bf16 v[10:13], v[142:145], v[216:219], v[10:13]
	v_mfma_f32_16x16x32_bf16 v[54:57], v[146:149], v[184:187], v[54:57]
	v_mfma_f32_16x16x32_bf16 v[50:53], v[170:173], v[184:187], v[50:53]
	v_mfma_f32_16x16x32_bf16 v[38:41], v[146:149], v[192:195], v[38:41]
	v_mfma_f32_16x16x32_bf16 v[34:37], v[170:173], v[192:195], v[34:37]
	v_mfma_f32_16x16x32_bf16 v[22:25], v[146:149], v[204:207], v[22:25]
	v_mfma_f32_16x16x32_bf16 v[18:21], v[170:173], v[204:207], v[18:21]
	v_mfma_f32_16x16x32_bf16 v[6:9], v[146:149], v[212:215], v[6:9]
	v_mfma_f32_16x16x32_bf16 v[2:5], v[170:173], v[212:215], v[2:5]
	v_mfma_f32_16x16x32_bf16 v[54:57], v[166:169], v[188:191], v[54:57]
	v_mfma_f32_16x16x32_bf16 v[50:53], v[174:177], v[188:191], v[50:53]
	v_mfma_f32_16x16x32_bf16 v[38:41], v[166:169], v[200:203], v[38:41]
	v_mfma_f32_16x16x32_bf16 v[34:37], v[174:177], v[200:203], v[34:37]
	v_mfma_f32_16x16x32_bf16 v[22:25], v[166:169], v[208:211], v[22:25]
	v_mfma_f32_16x16x32_bf16 v[18:21], v[174:177], v[208:211], v[18:21]
	v_mfma_f32_16x16x32_bf16 v[6:9], v[166:169], v[216:219], v[6:9]
	v_mfma_f32_16x16x32_bf16 v[2:5], v[174:177], v[216:219], v[2:5]
	s_barrier
	s_mov_b32 m0, s29
	s_nop 0
	global_load_lds_dwordx4 v[222:223], off
	s_mov_b32 m0, s39
	s_nop 0
	global_load_lds_dwordx4 v[224:225], off
	s_add_i32 s57, 0, 0x18000
	s_add_i32 s58, 0, 0x1c000
	v_add_u32_e32 v142, s57, v178
	v_add_u32_e32 v174, s58, v178
	ds_read_b128 v[130:133], v142
	ds_read_b128 v[134:137], v142 offset:1024
	ds_read_b128 v[138:141], v142 offset:2048
	ds_read_b128 v[142:145], v142 offset:3072
	ds_read_b128 v[146:149], v174
	ds_read_b128 v[166:169], v174 offset:1024
	ds_read_b128 v[170:173], v174 offset:2048
	ds_read_b128 v[174:177], v174 offset:3072
	s_add_u32 s36, s36, 0x80000
	s_addc_u32 s37, s37, 0
	s_mov_b32 m0, s40
	v_lshl_add_u64 v[226:227], s[36:37], 0, v[150:151]
	ds_read_b128 v[184:187], v182 offset:32768
	ds_read_b128 v[188:191], v182 offset:33792
	ds_read_b128 v[192:195], v182 offset:34816
	ds_read_b128 v[200:203], v182 offset:35840
	ds_read_b128 v[204:207], v182 offset:36864
	ds_read_b128 v[208:211], v182 offset:37888
	ds_read_b128 v[212:215], v182 offset:38912
	ds_read_b128 v[216:219], v182 offset:39936
	global_load_lds_dwordx4 v[226:227], off
	v_lshl_add_u64 v[226:227], s[36:37], 0, v[154:155]
	s_mov_b32 m0, s41
	s_nop 0
	global_load_lds_dwordx4 v[226:227], off
	s_waitcnt vmcnt(8)
	s_waitcnt lgkmcnt(0)
	s_barrier
; #define PG8_STAGE(bufoff, gbase, voff) do { _Pragma("unroll") for (int _i = 0; _i < 2; ++_i) \
;         __builtin_amdgcn_global_load_lds((const unsigned*)((const char*)(gbase) + (voff)[_i]), (PG8_LAS unsigned*)(lds + (bufoff) + ldsw + _i * 8192), 16, 0, 0); } while (0)
; #define PG8_LDA(dst, b, h) do { _Pragma("unroll") for (int m = 0; m < 4; ++m) _Pragma("unroll") for (int k = 0; k < 2; ++k) dst[m][k] = *(const PG8_LAS bf16x8*)(lds + PG8_SA(b, h) + aoff + m * 2048 + k * 1024); } while (0)
; #define PG8_MMA(ai, bj, At, Bt) do { __builtin_amdgcn_s_setprio(1); _Pragma("unroll") for (int m = 0; m < 4; ++m) _Pragma("unroll") for (int n = 0; n < 2; ++n) _Pragma("unroll") for (int k = 0; k < 2; ++k) \
;         acc[ai][bj][m][n] = __builtin_amdgcn_mfma_f32_16x16x32_bf16(Bt[n][k], At[m][k], acc[ai][bj][m][n], 0, 0, 0); __builtin_amdgcn_s_setprio(0); } while (0)
; #define PG8_WAIT_V(n) asm volatile("s_waitcnt vmcnt(" #n ")" ::: "memory")
; #define PG8_WAIT_L(n) asm volatile("s_waitcnt lgkmcnt(" #n ")" ::: "memory")
; #define PG8_BAR __builtin_amdgcn_s_barrier()
; #define PG8_SCHED __builtin_amdgcn_sched_barrier(0)
; template <class Epi, class Sched, bool ALIGN_EPI = false, bool SP2 = false>
; __device__ __forceinline__ void gemm_phase(PG8_LAS unsigned char* lds, const Gemm g, const Sched& S, const Epi& E) {
;     ...
;             PG8_WAIT_V(8); PG8_WAIT_L(0); PG8_BAR; PG8_MMA(0, 0, At, B0); PG8_MMA(0, 1, At, B1); PG8_BAR; PG8_SCHED;
;             PG8_LDA(At, 1, 1); PG8_STAGE(PG8_SB(1, 0), b3, voffB); PG8_STAGE(PG8_SB(1, 1), b3 + hstep, voffB); PG8_STAGE(PG8_SA(1, 0), a3, voffA);
;             PG8_WAIT_V(8); PG8_WAIT_L(0); PG8_BAR; PG8_MMA(1, 0, At, B0); PG8_MMA(1, 1, At, B1); PG8_BAR; PG8_SCHED;
	v_mfma_f32_16x16x32_bf16 v[126:129], v[130:133], v[184:187], v[126:129]
	v_mfma_f32_16x16x32_bf16 v[122:125], v[138:141], v[184:187], v[122:125]
	v_mfma_f32_16x16x32_bf16 v[110:113], v[130:133], v[192:195], v[110:113]
	v_mfma_f32_16x16x32_bf16 v[106:109], v[138:141], v[192:195], v[106:109]
	v_mfma_f32_16x16x32_bf16 v[94:97], v[130:133], v[204:207], v[94:97]
	v_mfma_f32_16x16x32_bf16 v[90:93], v[138:141], v[204:207], v[90:93]
	v_mfma_f32_16x16x32_bf16 v[78:81], v[130:133], v[212:215], v[78:81]
	v_mfma_f32_16x16x32_bf16 v[74:77], v[138:141], v[212:215], v[74:77]
	v_mfma_f32_16x16x32_bf16 v[126:129], v[134:137], v[188:191], v[126:129]
	v_mfma_f32_16x16x32_bf16 v[122:125], v[142:145], v[188:191], v[122:125]
	v_mfma_f32_16x16x32_bf16 v[110:113], v[134:137], v[200:203], v[110:113]
	v_mfma_f32_16x16x32_bf16 v[106:109], v[142:145], v[200:203], v[106:109]
	v_mfma_f32_16x16x32_bf16 v[94:97], v[134:137], v[208:211], v[94:97]
	v_mfma_f32_16x16x32_bf16 v[90:93], v[142:145], v[208:211], v[90:93]
	v_mfma_f32_16x16x32_bf16 v[78:81], v[134:137], v[216:219], v[78:81]
	v_mfma_f32_16x16x32_bf16 v[74:77], v[142:145], v[216:219], v[74:77]
	v_mfma_f32_16x16x32_bf16 v[118:121], v[146:149], v[184:187], v[118:121]
	v_mfma_f32_16x16x32_bf16 v[114:117], v[170:173], v[184:187], v[114:117]
	v_mfma_f32_16x16x32_bf16 v[102:105], v[146:149], v[192:195], v[102:105]
	v_mfma_f32_16x16x32_bf16 v[98:101], v[170:173], v[192:195], v[98:101]
	v_mfma_f32_16x16x32_bf16 v[86:89], v[146:149], v[204:207], v[86:89]
	v_mfma_f32_16x16x32_bf16 v[82:85], v[170:173], v[204:207], v[82:85]
	v_mfma_f32_16x16x32_bf16 v[70:73], v[146:149], v[212:215], v[70:73]
	v_mfma_f32_16x16x32_bf16 v[66:69], v[170:173], v[212:215], v[66:69]
	v_mfma_f32_16x16x32_bf16 v[118:121], v[166:169], v[188:191], v[118:121]
	v_mfma_f32_16x16x32_bf16 v[114:117], v[174:177], v[188:191], v[114:117]
	v_mfma_f32_16x16x32_bf16 v[102:105], v[166:169], v[200:203], v[102:105]
	v_mfma_f32_16x16x32_bf16 v[98:101], v[174:177], v[200:203], v[98:101]
	v_mfma_f32_16x16x32_bf16 v[86:89], v[166:169], v[208:211], v[86:89]
	v_mfma_f32_16x16x32_bf16 v[82:85], v[174:177], v[208:211], v[82:85]
	v_mfma_f32_16x16x32_bf16 v[70:73], v[166:169], v[216:219], v[70:73]
	v_mfma_f32_16x16x32_bf16 v[66:69], v[174:177], v[216:219], v[66:69]
	s_barrier
	s_add_i32 s36, s57, s38
	v_lshl_add_u64 v[196:197], v[196:197], 0, s[8:9]
	s_mov_b32 m0, s36
	ds_read_b128 v[184:187], v182 offset:49152
	ds_read_b128 v[188:191], v182 offset:50176
	ds_read_b128 v[192:195], v182 offset:51200
	ds_read_b128 v[200:203], v182 offset:52224
	ds_read_b128 v[204:207], v182 offset:53248
	ds_read_b128 v[208:211], v182 offset:54272
	ds_read_b128 v[212:215], v182 offset:55296
	ds_read_b128 v[216:219], v182 offset:56320
	global_load_lds_dwordx4 v[196:197], off
	s_add_i32 m0, s36, 0x2000
	s_add_u32 s34, s34, 0x80080
	v_lshl_add_u64 v[196:197], v[220:221], 0, s[8:9]
	s_addc_u32 s35, s35, 0
	s_add_i32 s36, s58, s38
	global_load_lds_dwordx4 v[196:197], off
	v_lshl_add_u64 v[196:197], s[34:35], 0, v[152:153]
	s_mov_b32 m0, s36
	s_nop 0
	global_load_lds_dwordx4 v[196:197], off
	v_lshl_add_u64 v[196:197], s[34:35], 0, v[156:157]
	s_add_i32 m0, s36, 0x2000
	s_nop 0
	global_load_lds_dwordx4 v[196:197], off
	s_waitcnt vmcnt(6)
	s_waitcnt lgkmcnt(0)
	s_barrier
	v_mfma_f32_16x16x32_bf16 v[62:65], v[130:133], v[184:187], v[62:65]
	v_mfma_f32_16x16x32_bf16 v[58:61], v[138:141], v[184:187], v[58:61]
	v_mfma_f32_16x16x32_bf16 v[46:49], v[130:133], v[192:195], v[46:49]
	v_mfma_f32_16x16x32_bf16 v[42:45], v[138:141], v[192:195], v[42:45]
	v_mfma_f32_16x16x32_bf16 v[30:33], v[130:133], v[204:207], v[30:33]
	v_mfma_f32_16x16x32_bf16 v[26:29], v[138:141], v[204:207], v[26:29]
	v_mfma_f32_16x16x32_bf16 v[14:17], v[130:133], v[212:215], v[14:17]
	v_mfma_f32_16x16x32_bf16 v[10:13], v[138:141], v[212:215], v[10:13]
	v_mfma_f32_16x16x32_bf16 v[62:65], v[134:137], v[188:191], v[62:65]
	v_mfma_f32_16x16x32_bf16 v[58:61], v[142:145], v[188:191], v[58:61]
	v_mfma_f32_16x16x32_bf16 v[46:49], v[134:137], v[200:203], v[46:49]
	v_mfma_f32_16x16x32_bf16 v[42:45], v[142:145], v[200:203], v[42:45]
	v_mfma_f32_16x16x32_bf16 v[30:33], v[134:137], v[208:211], v[30:33]
	v_mfma_f32_16x16x32_bf16 v[26:29], v[142:145], v[208:211], v[26:29]
	v_mfma_f32_16x16x32_bf16 v[14:17], v[134:137], v[216:219], v[14:17]
	v_mfma_f32_16x16x32_bf16 v[10:13], v[142:145], v[216:219], v[10:13]
	v_mfma_f32_16x16x32_bf16 v[54:57], v[146:149], v[184:187], v[54:57]
	v_mfma_f32_16x16x32_bf16 v[50:53], v[170:173], v[184:187], v[50:53]
	v_mfma_f32_16x16x32_bf16 v[38:41], v[146:149], v[192:195], v[38:41]
	v_mfma_f32_16x16x32_bf16 v[34:37], v[170:173], v[192:195], v[34:37]
	v_mfma_f32_16x16x32_bf16 v[22:25], v[146:149], v[204:207], v[22:25]
	v_mfma_f32_16x16x32_bf16 v[18:21], v[170:173], v[204:207], v[18:21]
	v_mfma_f32_16x16x32_bf16 v[6:9], v[146:149], v[212:215], v[6:9]
	v_mfma_f32_16x16x32_bf16 v[2:5], v[170:173], v[212:215], v[2:5]
	v_mfma_f32_16x16x32_bf16 v[54:57], v[166:169], v[188:191], v[54:57]
	v_mfma_f32_16x16x32_bf16 v[50:53], v[174:177], v[188:191], v[50:53]
	v_mfma_f32_16x16x32_bf16 v[38:41], v[166:169], v[200:203], v[38:41]
	v_mfma_f32_16x16x32_bf16 v[34:37], v[174:177], v[200:203], v[34:37]
	v_mfma_f32_16x16x32_bf16 v[22:25], v[166:169], v[208:211], v[22:25]
	v_mfma_f32_16x16x32_bf16 v[18:21], v[174:177], v[208:211], v[18:21]
	v_mfma_f32_16x16x32_bf16 v[6:9], v[166:169], v[216:219], v[6:9]
	v_mfma_f32_16x16x32_bf16 v[2:5], v[174:177], v[216:219], v[2:5]
	s_barrier
	s_add_i32 s56, s56, 2
	s_add_u32 s30, s30, 0x100
	s_addc_u32 s31, s31, 0
	s_add_u32 s52, s52, 0x100
	s_addc_u32 s53, s53, 0
	s_cmp_gt_u32 s56, 29
	s_cbranch_scc0 .LBB0_857
	s_and_b64 vcc, exec, s[10:11]
	s_cbranch_vccz .LBB0_860
	s_barrier

; #define PG8_STAGE(bufoff, gbase, voff) do { _Pragma("unroll") for (int _i = 0; _i < 2; ++_i) \
;         __builtin_amdgcn_global_load_lds((const unsigned*)((const char*)(gbase) + (voff)[_i]), (PG8_LAS unsigned*)(lds + (bufoff) + ldsw + _i * 8192), 16, 0, 0); } while (0)
; #define PG8_LDA(dst, b, h) do { _Pragma("unroll") for (int m = 0; m < 4; ++m) _Pragma("unroll") for (int k = 0; k < 2; ++k) dst[m][k] = *(const PG8_LAS bf16x8*)(lds + PG8_SA(b, h) + aoff + m * 2048 + k * 1024); } while (0)
; #define PG8_LDB(dst, b, h) do { _Pragma("unroll") for (int n = 0; n < 2; ++n) _Pragma("unroll") for (int k = 0; k < 2; ++k) dst[n][k] = *(const PG8_LAS bf16x8*)(lds + PG8_SB(b, h) + boff + n * 2048 + k * 1024); } while (0)
; #define PG8_MMA(ai, bj, At, Bt) do { __builtin_amdgcn_s_setprio(1); _Pragma("unroll") for (int m = 0; m < 4; ++m) _Pragma("unroll") for (int n = 0; n < 2; ++n) _Pragma("unroll") for (int k = 0; k < 2; ++k) \
;         acc[ai][bj][m][n] = __builtin_amdgcn_mfma_f32_16x16x32_bf16(Bt[n][k], At[m][k], acc[ai][bj][m][n], 0, 0, 0); __builtin_amdgcn_s_setprio(0); } while (0)
; #define PG8_WAIT_V(n) asm volatile("s_waitcnt vmcnt(" #n ")" ::: "memory")
; #define PG8_WAIT_L(n) asm volatile("s_waitcnt lgkmcnt(" #n ")" ::: "memory")
; template <class Epi, class Sched, bool ALIGN_EPI = false, bool SP2 = false>
; __device__ __forceinline__ void gemm_phase(PG8_LAS unsigned char* lds, const Gemm g, const Sched& S, const Epi& E) {
;     ...
;             const bool last = (t == nt - 2);
;             const char* a1 = cA + (size_t)(t + 1) * kstep;
;             const char* a2 = last ? nA : cA + (size_t)(t + 2) * kstep; const char* b2 = last ? nB : cB + (size_t)(t + 2) * kstep;
;             const char* a3 = a2 + kstep; const char* b3 = b2 + kstep;
;             if (last && has_next) S.a_ready(nxt);
;             if constexpr (SP2) {
;             PG8_LDB(B0, 0, 0); PG8_LDB(B1, 0, 1); PG8_SCHED; PG8_LDA(At, 0, 0); PG8_STAGE(PG8_SA(1, 1), a1 + hstep, voffA);
;             PG8_WAIT_V(8); PG8_WAIT_L(0); PG8_BAR; PG8_MMA(0, 0, At, B0); PG8_MMA(0, 1, At, B1); PG8_BAR; PG8_SCHED;
;             PG8_LDA(At, 0, 1); PG8_STAGE(PG8_SB(0, 0), b2, voffB); PG8_STAGE(PG8_SB(0, 1), b2 + hstep, voffB); PG8_STAGE(PG8_SA(0, 0), a2, voffA);
;             PG8_WAIT_V(8); PG8_WAIT_L(0); PG8_BAR; PG8_MMA(1, 0, At, B0); PG8_MMA(1, 1, At, B1); PG8_BAR; PG8_SCHED;
.LBB0_884:
	s_add_u32 s34, s30, 0xfff80000
	s_addc_u32 s35, s31, -1
	v_lshl_add_u64 v[208:209], s[34:35], 0, v[178:179]
	s_mov_b32 m0, s43
	s_nop 0
	global_load_lds_dwordx4 v[208:209], off
	v_lshl_add_u64 v[208:209], s[34:35], 0, v[182:183]
	s_mov_b32 m0, s44
	s_nop 0
	global_load_lds_dwordx4 v[208:209], off
	s_add_u32 s34, s34, 0x80
	s_addc_u32 s35, s35, 0
	ds_read_b128 v[130:133], v211
	ds_read_b128 v[134:137], v211 offset:1024
	ds_read_b128 v[138:141], v211 offset:2048
	ds_read_b128 v[142:145], v211 offset:3072
	ds_read_b128 v[146:149], v212
	ds_read_b128 v[150:153], v212 offset:1024
	ds_read_b128 v[154:157], v212 offset:2048
	ds_read_b128 v[158:161], v212 offset:3072
	s_cmp_eq_u32 s56, 28
	s_cselect_b32 s37, s15, s35
	s_cselect_b32 s36, s50, s34
	s_cselect_b32 s35, s13, s53
	s_cselect_b32 s34, s51, s52
	v_lshl_add_u64 v[208:209], s[30:31], 0, v[186:187]
	s_add_i32 m0, s29, 0xc000
	ds_read_b128 v[162:165], v213
	ds_read_b128 v[166:169], v213 offset:1024
	ds_read_b128 v[170:173], v213 offset:2048
	ds_read_b128 v[174:177], v213 offset:3072
	ds_read_b128 v[194:197], v213 offset:4096
	ds_read_b128 v[200:203], v213 offset:5120
	ds_read_b128 v[204:207], v213 offset:6144
	ds_read_b128 v[214:217], v213 offset:7168
	global_load_lds_dwordx4 v[208:209], off
	v_lshl_add_u64 v[208:209], s[30:31], 0, v[188:189]
	s_add_i32 m0, s29, 0xe000
	s_nop 0
	global_load_lds_dwordx4 v[208:209], off
	s_waitcnt vmcnt(8)
	s_waitcnt lgkmcnt(0)
	s_barrier
	v_mfma_f32_16x16x32_bf16 v[126:129], v[130:133], v[162:165], v[126:129]
	v_mfma_f32_16x16x32_bf16 v[122:125], v[138:141], v[162:165], v[122:125]
	v_mfma_f32_16x16x32_bf16 v[110:113], v[130:133], v[170:173], v[110:113]
	v_mfma_f32_16x16x32_bf16 v[106:109], v[138:141], v[170:173], v[106:109]
	v_mfma_f32_16x16x32_bf16 v[94:97], v[130:133], v[194:197], v[94:97]
	v_mfma_f32_16x16x32_bf16 v[90:93], v[138:141], v[194:197], v[90:93]
	v_mfma_f32_16x16x32_bf16 v[78:81], v[130:133], v[204:207], v[78:81]
	v_mfma_f32_16x16x32_bf16 v[74:77], v[138:141], v[204:207], v[74:77]
	v_mfma_f32_16x16x32_bf16 v[126:129], v[134:137], v[166:169], v[126:129]
	v_mfma_f32_16x16x32_bf16 v[122:125], v[142:145], v[166:169], v[122:125]
	v_mfma_f32_16x16x32_bf16 v[110:113], v[134:137], v[174:177], v[110:113]
	v_mfma_f32_16x16x32_bf16 v[106:109], v[142:145], v[174:177], v[106:109]
	v_mfma_f32_16x16x32_bf16 v[94:97], v[134:137], v[200:203], v[94:97]
	v_mfma_f32_16x16x32_bf16 v[90:93], v[142:145], v[200:203], v[90:93]
	v_mfma_f32_16x16x32_bf16 v[78:81], v[134:137], v[214:217], v[78:81]
	v_mfma_f32_16x16x32_bf16 v[74:77], v[142:145], v[214:217], v[74:77]
	v_mfma_f32_16x16x32_bf16 v[118:121], v[146:149], v[162:165], v[118:121]
	v_mfma_f32_16x16x32_bf16 v[114:117], v[154:157], v[162:165], v[114:117]
	v_mfma_f32_16x16x32_bf16 v[102:105], v[146:149], v[170:173], v[102:105]
	v_mfma_f32_16x16x32_bf16 v[98:101], v[154:157], v[170:173], v[98:101]
	v_mfma_f32_16x16x32_bf16 v[86:89], v[146:149], v[194:197], v[86:89]
	v_mfma_f32_16x16x32_bf16 v[82:85], v[154:157], v[194:197], v[82:85]
	v_mfma_f32_16x16x32_bf16 v[70:73], v[146:149], v[204:207], v[70:73]
	v_mfma_f32_16x16x32_bf16 v[66:69], v[154:157], v[204:207], v[66:69]
	v_mfma_f32_16x16x32_bf16 v[118:121], v[150:153], v[166:169], v[118:121]
	v_mfma_f32_16x16x32_bf16 v[114:117], v[158:161], v[166:169], v[114:117]
	v_mfma_f32_16x16x32_bf16 v[102:105], v[150:153], v[174:177], v[102:105]
	v_mfma_f32_16x16x32_bf16 v[98:101], v[158:161], v[174:177], v[98:101]
	v_mfma_f32_16x16x32_bf16 v[86:89], v[150:153], v[200:203], v[86:89]
	v_mfma_f32_16x16x32_bf16 v[82:85], v[158:161], v[200:203], v[82:85]
	v_mfma_f32_16x16x32_bf16 v[70:73], v[150:153], v[214:217], v[70:73]
	v_mfma_f32_16x16x32_bf16 v[66:69], v[158:161], v[214:217], v[66:69]
	s_barrier
	s_add_i32 s57, s46, s38
	v_lshl_add_u64 v[208:209], s[34:35], 0, v[180:181]
	s_mov_b32 m0, s57
	ds_read_b128 v[162:165], v213 offset:16384
	ds_read_b128 v[166:169], v213 offset:17408
	ds_read_b128 v[170:173], v213 offset:18432
	ds_read_b128 v[174:177], v213 offset:19456
	ds_read_b128 v[194:197], v213 offset:20480
	ds_read_b128 v[200:203], v213 offset:21504
	ds_read_b128 v[204:207], v213 offset:22528
	ds_read_b128 v[214:217], v213 offset:23552
	global_load_lds_dwordx4 v[208:209], off
	s_add_i32 m0, s57, 0x2000
	s_add_u32 s58, s34, 0x80000
	v_lshl_add_u64 v[218:219], s[34:35], 0, v[184:185]
	s_addc_u32 s59, s35, 0
	s_add_i32 s57, s47, s38
	global_load_lds_dwordx4 v[218:219], off
	v_lshl_add_u64 v[220:221], s[58:59], 0, v[180:181]
	s_mov_b32 m0, s57
	v_lshl_add_u64 v[222:223], s[36:37], 0, v[182:183]
	global_load_lds_dwordx4 v[220:221], off
	v_lshl_add_u64 v[220:221], s[58:59], 0, v[184:185]
	s_add_i32 m0, s57, 0x2000
	s_nop 0
	global_load_lds_dwordx4 v[220:221], off
	v_lshl_add_u64 v[220:221], s[36:37], 0, v[178:179]
	s_waitcnt vmcnt(6)
	s_waitcnt lgkmcnt(0)
	s_barrier
; #define PG8_STAGE(bufoff, gbase, voff) do { _Pragma("unroll") for (int _i = 0; _i < 2; ++_i) \
;         __builtin_amdgcn_global_load_lds((const unsigned*)((const char*)(gbase) + (voff)[_i]), (PG8_LAS unsigned*)(lds + (bufoff) + ldsw + _i * 8192), 16, 0, 0); } while (0)
; #define PG8_LDA(dst, b, h) do { _Pragma("unroll") for (int m = 0; m < 4; ++m) _Pragma("unroll") for (int k = 0; k < 2; ++k) dst[m][k] = *(const PG8_LAS bf16x8*)(lds + PG8_SA(b, h) + aoff + m * 2048 + k * 1024); } while (0)
; #define PG8_LDB(dst, b, h) do { _Pragma("unroll") for (int n = 0; n < 2; ++n) _Pragma("unroll") for (int k = 0; k < 2; ++k) dst[n][k] = *(const PG8_LAS bf16x8*)(lds + PG8_SB(b, h) + boff + n * 2048 + k * 1024); } while (0)
; #define PG8_MMA(ai, bj, At, Bt) do { __builtin_amdgcn_s_setprio(1); _Pragma("unroll") for (int m = 0; m < 4; ++m) _Pragma("unroll") for (int n = 0; n < 2; ++n) _Pragma("unroll") for (int k = 0; k < 2; ++k) \
;         acc[ai][bj][m][n] = __builtin_amdgcn_mfma_f32_16x16x32_bf16(Bt[n][k], At[m][k], acc[ai][bj][m][n], 0, 0, 0); __builtin_amdgcn_s_setprio(0); } while (0)
; #define PG8_WAIT_V(n) asm volatile("s_waitcnt vmcnt(" #n ")" ::: "memory")
; #define PG8_WAIT_L(n) asm volatile("s_waitcnt lgkmcnt(" #n ")" ::: "memory")
; #define PG8_BAR __builtin_amdgcn_s_barrier()
; #define PG8_SCHED __builtin_amdgcn_sched_barrier(0)
; template <class Epi, class Sched, bool ALIGN_EPI = false, bool SP2 = false>
; __device__ __forceinline__ void gemm_phase(PG8_LAS unsigned char* lds, const Gemm g, const Sched& S, const Epi& E) {
;     ...
;             PG8_WAIT_V(8); PG8_WAIT_L(0); PG8_BAR; PG8_MMA(1, 0, At, B0); PG8_MMA(1, 1, At, B1); PG8_BAR; PG8_SCHED;
;             PG8_LDB(B0, 1, 0); PG8_LDB(B1, 1, 1); PG8_SCHED; PG8_LDA(At, 1, 0); PG8_STAGE(PG8_SA(0, 1), a2 + hstep, voffA);
;             PG8_WAIT_V(8); PG8_WAIT_L(0); PG8_BAR; PG8_MMA(0, 0, At, B0); PG8_MMA(0, 1, At, B1); PG8_BAR; PG8_SCHED;
	v_mfma_f32_16x16x32_bf16 v[62:65], v[130:133], v[162:165], v[62:65]
	v_mfma_f32_16x16x32_bf16 v[58:61], v[138:141], v[162:165], v[58:61]
	v_mfma_f32_16x16x32_bf16 v[46:49], v[130:133], v[170:173], v[46:49]
	v_mfma_f32_16x16x32_bf16 v[42:45], v[138:141], v[170:173], v[42:45]
	v_mfma_f32_16x16x32_bf16 v[30:33], v[130:133], v[194:197], v[30:33]
	v_mfma_f32_16x16x32_bf16 v[26:29], v[138:141], v[194:197], v[26:29]
	v_mfma_f32_16x16x32_bf16 v[14:17], v[130:133], v[204:207], v[14:17]
	v_mfma_f32_16x16x32_bf16 v[10:13], v[138:141], v[204:207], v[10:13]
	v_mfma_f32_16x16x32_bf16 v[62:65], v[134:137], v[166:169], v[62:65]
	v_mfma_f32_16x16x32_bf16 v[58:61], v[142:145], v[166:169], v[58:61]
	v_mfma_f32_16x16x32_bf16 v[46:49], v[134:137], v[174:177], v[46:49]
	v_mfma_f32_16x16x32_bf16 v[42:45], v[142:145], v[174:177], v[42:45]
	v_mfma_f32_16x16x32_bf16 v[30:33], v[134:137], v[200:203], v[30:33]
	v_mfma_f32_16x16x32_bf16 v[26:29], v[142:145], v[200:203], v[26:29]
	v_mfma_f32_16x16x32_bf16 v[14:17], v[134:137], v[214:217], v[14:17]
	v_mfma_f32_16x16x32_bf16 v[10:13], v[142:145], v[214:217], v[10:13]
	v_mfma_f32_16x16x32_bf16 v[54:57], v[146:149], v[162:165], v[54:57]
	v_mfma_f32_16x16x32_bf16 v[50:53], v[154:157], v[162:165], v[50:53]
	v_mfma_f32_16x16x32_bf16 v[38:41], v[146:149], v[170:173], v[38:41]
	v_mfma_f32_16x16x32_bf16 v[34:37], v[154:157], v[170:173], v[34:37]
	v_mfma_f32_16x16x32_bf16 v[22:25], v[146:149], v[194:197], v[22:25]
	v_mfma_f32_16x16x32_bf16 v[18:21], v[154:157], v[194:197], v[18:21]
	v_mfma_f32_16x16x32_bf16 v[6:9], v[146:149], v[204:207], v[6:9]
	v_mfma_f32_16x16x32_bf16 v[2:5], v[154:157], v[204:207], v[2:5]
	v_mfma_f32_16x16x32_bf16 v[54:57], v[150:153], v[166:169], v[54:57]
	v_mfma_f32_16x16x32_bf16 v[50:53], v[158:161], v[166:169], v[50:53]
	v_mfma_f32_16x16x32_bf16 v[38:41], v[150:153], v[174:177], v[38:41]
	v_mfma_f32_16x16x32_bf16 v[34:37], v[158:161], v[174:177], v[34:37]
	v_mfma_f32_16x16x32_bf16 v[22:25], v[150:153], v[200:203], v[22:25]
	v_mfma_f32_16x16x32_bf16 v[18:21], v[158:161], v[200:203], v[18:21]
	v_mfma_f32_16x16x32_bf16 v[6:9], v[150:153], v[214:217], v[6:9]
	v_mfma_f32_16x16x32_bf16 v[2:5], v[158:161], v[214:217], v[2:5]
	s_barrier
	s_mov_b32 m0, s29
	s_nop 0
	global_load_lds_dwordx4 v[220:221], off
	s_mov_b32 m0, s39
	s_nop 0
	global_load_lds_dwordx4 v[222:223], off
	s_add_i32 s57, 0, 0x18000
	s_add_i32 s58, 0, 0x1c000
	v_add_u32_e32 v142, s57, v199
	v_add_u32_e32 v158, s58, v199
	ds_read_b128 v[130:133], v142
	ds_read_b128 v[134:137], v142 offset:1024
	ds_read_b128 v[138:141], v142 offset:2048
	ds_read_b128 v[142:145], v142 offset:3072
	ds_read_b128 v[146:149], v158
	ds_read_b128 v[150:153], v158 offset:1024
	ds_read_b128 v[154:157], v158 offset:2048
	ds_read_b128 v[158:161], v158 offset:3072
	s_add_u32 s36, s36, 0x80000
	s_addc_u32 s37, s37, 0
	s_mov_b32 m0, s40
	v_lshl_add_u64 v[224:225], s[36:37], 0, v[178:179]
	ds_read_b128 v[162:165], v213 offset:32768
	ds_read_b128 v[166:169], v213 offset:33792
	ds_read_b128 v[170:173], v213 offset:34816
	ds_read_b128 v[174:177], v213 offset:35840
	ds_read_b128 v[194:197], v213 offset:36864
	ds_read_b128 v[200:203], v213 offset:37888
	ds_read_b128 v[204:207], v213 offset:38912
	ds_read_b128 v[214:217], v213 offset:39936
	global_load_lds_dwordx4 v[224:225], off
	v_lshl_add_u64 v[224:225], s[36:37], 0, v[182:183]
	s_mov_b32 m0, s41
	s_nop 0
	global_load_lds_dwordx4 v[224:225], off
	s_waitcnt vmcnt(8)
	s_waitcnt lgkmcnt(0)
	s_barrier
; #define PG8_STAGE(bufoff, gbase, voff) do { _Pragma("unroll") for (int _i = 0; _i < 2; ++_i) \
;         __builtin_amdgcn_global_load_lds((const unsigned*)((const char*)(gbase) + (voff)[_i]), (PG8_LAS unsigned*)(lds + (bufoff) + ldsw + _i * 8192), 16, 0, 0); } while (0)
; #define PG8_LDA(dst, b, h) do { _Pragma("unroll") for (int m = 0; m < 4; ++m) _Pragma("unroll") for (int k = 0; k < 2; ++k) dst[m][k] = *(const PG8_LAS bf16x8*)(lds + PG8_SA(b, h) + aoff + m * 2048 + k * 1024); } while (0)
; #define PG8_MMA(ai, bj, At, Bt) do { __builtin_amdgcn_s_setprio(1); _Pragma("unroll") for (int m = 0; m < 4; ++m) _Pragma("unroll") for (int n = 0; n < 2; ++n) _Pragma("unroll") for (int k = 0; k < 2; ++k) \
;         acc[ai][bj][m][n] = __builtin_amdgcn_mfma_f32_16x16x32_bf16(Bt[n][k], At[m][k], acc[ai][bj][m][n], 0, 0, 0); __builtin_amdgcn_s_setprio(0); } while (0)
; #define PG8_WAIT_V(n) asm volatile("s_waitcnt vmcnt(" #n ")" ::: "memory")
; #define PG8_WAIT_L(n) asm volatile("s_waitcnt lgkmcnt(" #n ")" ::: "memory")
; #define PG8_BAR __builtin_amdgcn_s_barrier()
; #define PG8_SCHED __builtin_amdgcn_sched_barrier(0)
; template <class Epi, class Sched, bool ALIGN_EPI = false, bool SP2 = false>
; __device__ __forceinline__ void gemm_phase(PG8_LAS unsigned char* lds, const Gemm g, const Sched& S, const Epi& E) {
;     ...
;             PG8_WAIT_V(8); PG8_WAIT_L(0); PG8_BAR; PG8_MMA(0, 0, At, B0); PG8_MMA(0, 1, At, B1); PG8_BAR; PG8_SCHED;
;             PG8_LDA(At, 1, 1); PG8_STAGE(PG8_SB(1, 0), b3, voffB); PG8_STAGE(PG8_SB(1, 1), b3 + hstep, voffB); PG8_STAGE(PG8_SA(1, 0), a3, voffA);
;             PG8_WAIT_V(8); PG8_WAIT_L(0); PG8_BAR; PG8_MMA(1, 0, At, B0); PG8_MMA(1, 1, At, B1); PG8_BAR; PG8_SCHED;
	v_mfma_f32_16x16x32_bf16 v[126:129], v[130:133], v[162:165], v[126:129]
	v_mfma_f32_16x16x32_bf16 v[122:125], v[138:141], v[162:165], v[122:125]
	v_mfma_f32_16x16x32_bf16 v[110:113], v[130:133], v[170:173], v[110:113]
	v_mfma_f32_16x16x32_bf16 v[106:109], v[138:141], v[170:173], v[106:109]
	v_mfma_f32_16x16x32_bf16 v[94:97], v[130:133], v[194:197], v[94:97]
	v_mfma_f32_16x16x32_bf16 v[90:93], v[138:141], v[194:197], v[90:93]
	v_mfma_f32_16x16x32_bf16 v[78:81], v[130:133], v[204:207], v[78:81]
	v_mfma_f32_16x16x32_bf16 v[74:77], v[138:141], v[204:207], v[74:77]
	v_mfma_f32_16x16x32_bf16 v[126:129], v[134:137], v[166:169], v[126:129]
	v_mfma_f32_16x16x32_bf16 v[122:125], v[142:145], v[166:169], v[122:125]
	v_mfma_f32_16x16x32_bf16 v[110:113], v[134:137], v[174:177], v[110:113]
	v_mfma_f32_16x16x32_bf16 v[106:109], v[142:145], v[174:177], v[106:109]
	v_mfma_f32_16x16x32_bf16 v[94:97], v[134:137], v[200:203], v[94:97]
	v_mfma_f32_16x16x32_bf16 v[90:93], v[142:145], v[200:203], v[90:93]
	v_mfma_f32_16x16x32_bf16 v[78:81], v[134:137], v[214:217], v[78:81]
	v_mfma_f32_16x16x32_bf16 v[74:77], v[142:145], v[214:217], v[74:77]
	v_mfma_f32_16x16x32_bf16 v[118:121], v[146:149], v[162:165], v[118:121]
	v_mfma_f32_16x16x32_bf16 v[114:117], v[154:157], v[162:165], v[114:117]
	v_mfma_f32_16x16x32_bf16 v[102:105], v[146:149], v[170:173], v[102:105]
	v_mfma_f32_16x16x32_bf16 v[98:101], v[154:157], v[170:173], v[98:101]
	v_mfma_f32_16x16x32_bf16 v[86:89], v[146:149], v[194:197], v[86:89]
	v_mfma_f32_16x16x32_bf16 v[82:85], v[154:157], v[194:197], v[82:85]
	v_mfma_f32_16x16x32_bf16 v[70:73], v[146:149], v[204:207], v[70:73]
	v_mfma_f32_16x16x32_bf16 v[66:69], v[154:157], v[204:207], v[66:69]
	v_mfma_f32_16x16x32_bf16 v[118:121], v[150:153], v[166:169], v[118:121]
	v_mfma_f32_16x16x32_bf16 v[114:117], v[158:161], v[166:169], v[114:117]
	v_mfma_f32_16x16x32_bf16 v[102:105], v[150:153], v[174:177], v[102:105]
	v_mfma_f32_16x16x32_bf16 v[98:101], v[158:161], v[174:177], v[98:101]
	v_mfma_f32_16x16x32_bf16 v[86:89], v[150:153], v[200:203], v[86:89]
	v_mfma_f32_16x16x32_bf16 v[82:85], v[158:161], v[200:203], v[82:85]
	v_mfma_f32_16x16x32_bf16 v[70:73], v[150:153], v[214:217], v[70:73]
	v_mfma_f32_16x16x32_bf16 v[66:69], v[158:161], v[214:217], v[66:69]
	s_barrier
	s_add_i32 s36, s57, s38
	v_lshl_add_u64 v[208:209], v[208:209], 0, s[8:9]
	s_mov_b32 m0, s36
	ds_read_b128 v[162:165], v213 offset:49152
	ds_read_b128 v[166:169], v213 offset:50176
	ds_read_b128 v[170:173], v213 offset:51200
	ds_read_b128 v[174:177], v213 offset:52224
	ds_read_b128 v[194:197], v213 offset:53248
	ds_read_b128 v[200:203], v213 offset:54272
	ds_read_b128 v[204:207], v213 offset:55296
	ds_read_b128 v[214:217], v213 offset:56320
	global_load_lds_dwordx4 v[208:209], off
	s_add_i32 m0, s36, 0x2000
	s_add_u32 s34, s34, 0x80080
	v_lshl_add_u64 v[208:209], v[218:219], 0, s[8:9]
	s_addc_u32 s35, s35, 0
	s_add_i32 s36, s58, s38
	global_load_lds_dwordx4 v[208:209], off
	v_lshl_add_u64 v[208:209], s[34:35], 0, v[180:181]
	s_mov_b32 m0, s36
	s_nop 0
	global_load_lds_dwordx4 v[208:209], off
	v_lshl_add_u64 v[208:209], s[34:35], 0, v[184:185]
	s_add_i32 m0, s36, 0x2000
	s_nop 0
	global_load_lds_dwordx4 v[208:209], off
	s_waitcnt vmcnt(6)
	s_waitcnt lgkmcnt(0)
	s_barrier
	v_mfma_f32_16x16x32_bf16 v[62:65], v[130:133], v[162:165], v[62:65]
	v_mfma_f32_16x16x32_bf16 v[58:61], v[138:141], v[162:165], v[58:61]
	v_mfma_f32_16x16x32_bf16 v[46:49], v[130:133], v[170:173], v[46:49]
	v_mfma_f32_16x16x32_bf16 v[42:45], v[138:141], v[170:173], v[42:45]
	v_mfma_f32_16x16x32_bf16 v[30:33], v[130:133], v[194:197], v[30:33]
	v_mfma_f32_16x16x32_bf16 v[26:29], v[138:141], v[194:197], v[26:29]
	v_mfma_f32_16x16x32_bf16 v[14:17], v[130:133], v[204:207], v[14:17]
	v_mfma_f32_16x16x32_bf16 v[10:13], v[138:141], v[204:207], v[10:13]
	v_mfma_f32_16x16x32_bf16 v[62:65], v[134:137], v[166:169], v[62:65]
	v_mfma_f32_16x16x32_bf16 v[58:61], v[142:145], v[166:169], v[58:61]
	v_mfma_f32_16x16x32_bf16 v[46:49], v[134:137], v[174:177], v[46:49]
	v_mfma_f32_16x16x32_bf16 v[42:45], v[142:145], v[174:177], v[42:45]
	v_mfma_f32_16x16x32_bf16 v[30:33], v[134:137], v[200:203], v[30:33]
	v_mfma_f32_16x16x32_bf16 v[26:29], v[142:145], v[200:203], v[26:29]
	v_mfma_f32_16x16x32_bf16 v[14:17], v[134:137], v[214:217], v[14:17]
	v_mfma_f32_16x16x32_bf16 v[10:13], v[142:145], v[214:217], v[10:13]
	v_mfma_f32_16x16x32_bf16 v[54:57], v[146:149], v[162:165], v[54:57]
	v_mfma_f32_16x16x32_bf16 v[50:53], v[154:157], v[162:165], v[50:53]
	v_mfma_f32_16x16x32_bf16 v[38:41], v[146:149], v[170:173], v[38:41]
	v_mfma_f32_16x16x32_bf16 v[34:37], v[154:157], v[170:173], v[34:37]
	v_mfma_f32_16x16x32_bf16 v[22:25], v[146:149], v[194:197], v[22:25]
	v_mfma_f32_16x16x32_bf16 v[18:21], v[154:157], v[194:197], v[18:21]
	v_mfma_f32_16x16x32_bf16 v[6:9], v[146:149], v[204:207], v[6:9]
	v_mfma_f32_16x16x32_bf16 v[2:5], v[154:157], v[204:207], v[2:5]
	v_mfma_f32_16x16x32_bf16 v[54:57], v[150:153], v[166:169], v[54:57]
	v_mfma_f32_16x16x32_bf16 v[50:53], v[158:161], v[166:169], v[50:53]
	v_mfma_f32_16x16x32_bf16 v[38:41], v[150:153], v[174:177], v[38:41]
	v_mfma_f32_16x16x32_bf16 v[34:37], v[158:161], v[174:177], v[34:37]
	v_mfma_f32_16x16x32_bf16 v[22:25], v[150:153], v[200:203], v[22:25]
	v_mfma_f32_16x16x32_bf16 v[18:21], v[158:161], v[200:203], v[18:21]
	v_mfma_f32_16x16x32_bf16 v[6:9], v[150:153], v[214:217], v[6:9]
	v_mfma_f32_16x16x32_bf16 v[2:5], v[158:161], v[214:217], v[2:5]
	s_barrier
	s_add_i32 s56, s56, 2
	s_add_u32 s30, s30, 0x100
	s_addc_u32 s31, s31, 0
	s_add_u32 s52, s52, 0x100
	s_addc_u32 s53, s53, 0
	s_cmp_gt_u32 s56, 29
	s_cbranch_scc0 .LBB0_884
	s_and_b64 vcc, exec, s[10:11]
	s_cbranch_vccz .LBB0_887
	s_barrier

; #define PG8_STAGE(bufoff, gbase, voff) do { _Pragma("unroll") for (int _i = 0; _i < 2; ++_i) \
;         __builtin_amdgcn_global_load_lds((const unsigned*)((const char*)(gbase) + (voff)[_i]), (PG8_LAS unsigned*)(lds + (bufoff) + ldsw + _i * 8192), 16, 0, 0); } while (0)
; #define PG8_LDA(dst, b, h) do { _Pragma("unroll") for (int m = 0; m < 4; ++m) _Pragma("unroll") for (int k = 0; k < 2; ++k) dst[m][k] = *(const PG8_LAS bf16x8*)(lds + PG8_SA(b, h) + aoff + m * 2048 + k * 1024); } while (0)
; #define PG8_LDB(dst, b, h) do { _Pragma("unroll") for (int n = 0; n < 2; ++n) _Pragma("unroll") for (int k = 0; k < 2; ++k) dst[n][k] = *(const PG8_LAS bf16x8*)(lds + PG8_SB(b, h) + boff + n * 2048 + k * 1024); } while (0)
; #define PG8_MMA(ai, bj, At, Bt) do { __builtin_amdgcn_s_setprio(1); _Pragma("unroll") for (int m = 0; m < 4; ++m) _Pragma("unroll") for (int n = 0; n < 2; ++n) _Pragma("unroll") for (int k = 0; k < 2; ++k) \
;         acc[ai][bj][m][n] = __builtin_amdgcn_mfma_f32_16x16x32_bf16(Bt[n][k], At[m][k], acc[ai][bj][m][n], 0, 0, 0); __builtin_amdgcn_s_setprio(0); } while (0)
; #define PG8_WAIT_V(n) asm volatile("s_waitcnt vmcnt(" #n ")" ::: "memory")
; #define PG8_WAIT_L(n) asm volatile("s_waitcnt lgkmcnt(" #n ")" ::: "memory")
; template <class Epi, class Sched, bool ALIGN_EPI = false, bool SP2 = false>
; __device__ __forceinline__ void gemm_phase(PG8_LAS unsigned char* lds, const Gemm g, const Sched& S, const Epi& E) {
;     ...
;             const bool last = (t == nt - 2);
;             const char* a1 = cA + (size_t)(t + 1) * kstep;
;             const char* a2 = last ? nA : cA + (size_t)(t + 2) * kstep; const char* b2 = last ? nB : cB + (size_t)(t + 2) * kstep;
;             const char* a3 = a2 + kstep; const char* b3 = b2 + kstep;
;             if (last && has_next) S.a_ready(nxt);
;             if constexpr (SP2) {
;             PG8_LDB(B0, 0, 0); PG8_LDB(B1, 0, 1); PG8_SCHED; PG8_LDA(At, 0, 0); PG8_STAGE(PG8_SA(1, 1), a1 + hstep, voffA);
;             PG8_WAIT_V(8); PG8_WAIT_L(0); PG8_BAR; PG8_MMA(0, 0, At, B0); PG8_MMA(0, 1, At, B1); PG8_BAR; PG8_SCHED;
;             PG8_LDA(At, 0, 1); PG8_STAGE(PG8_SB(0, 0), b2, voffB); PG8_STAGE(PG8_SB(0, 1), b2 + hstep, voffB); PG8_STAGE(PG8_SA(0, 0), a2, voffA);
;             PG8_WAIT_V(8); PG8_WAIT_L(0); PG8_BAR; PG8_MMA(1, 0, At, B0); PG8_MMA(1, 1, At, B1); PG8_BAR; PG8_SCHED;
.LBB0_959:
	s_add_u32 s30, s28, 0xfff00000
	s_addc_u32 s31, s29, -1
	v_lshl_add_u64 v[196:197], s[30:31], 0, v[138:139]
	s_mov_b32 m0, s41
	s_nop 0
	global_load_lds_dwordx4 v[196:197], off
	v_lshl_add_u64 v[196:197], s[30:31], 0, v[142:143]
	s_mov_b32 m0, s42
	s_nop 0
	global_load_lds_dwordx4 v[196:197], off
	s_add_u32 s30, s30, 0x80
	s_addc_u32 s31, s31, 0
	ds_read_b128 v[130:133], v164
	ds_read_b128 v[134:137], v164 offset:1024
	ds_read_b128 v[154:157], v164 offset:2048
	ds_read_b128 v[158:161], v164 offset:3072
	ds_read_b128 v[168:171], v165
	ds_read_b128 v[172:175], v165 offset:1024
	ds_read_b128 v[176:179], v165 offset:2048
	ds_read_b128 v[180:183], v165 offset:3072
	s_cmp_eq_u32 s51, 60
	s_cselect_b32 s35, s13, s31
	s_cselect_b32 s34, s47, s30
	s_cselect_b32 s31, s11, s50
	s_cselect_b32 s30, s48, s49
	v_lshl_add_u64 v[196:197], s[28:29], 0, v[146:147]
	s_add_i32 m0, s27, 0xc000
	ds_read_b128 v[184:187], v166
	ds_read_b128 v[188:191], v166 offset:1024
	ds_read_b128 v[192:195], v166 offset:2048
	ds_read_b128 v[200:203], v166 offset:3072
	ds_read_b128 v[204:207], v166 offset:4096
	ds_read_b128 v[208:211], v166 offset:5120
	ds_read_b128 v[212:215], v166 offset:6144
	ds_read_b128 v[216:219], v166 offset:7168
	global_load_lds_dwordx4 v[196:197], off
	v_lshl_add_u64 v[196:197], s[28:29], 0, v[148:149]
	s_add_i32 m0, s27, 0xe000
	s_nop 0
	global_load_lds_dwordx4 v[196:197], off
	s_waitcnt vmcnt(8)
	s_waitcnt lgkmcnt(0)
	s_barrier
	v_mfma_f32_16x16x32_bf16 v[126:129], v[130:133], v[184:187], v[126:129]
	v_mfma_f32_16x16x32_bf16 v[122:125], v[154:157], v[184:187], v[122:125]
	v_mfma_f32_16x16x32_bf16 v[118:121], v[130:133], v[192:195], v[118:121]
	v_mfma_f32_16x16x32_bf16 v[114:117], v[154:157], v[192:195], v[114:117]
	v_mfma_f32_16x16x32_bf16 v[110:113], v[130:133], v[204:207], v[110:113]
	v_mfma_f32_16x16x32_bf16 v[102:105], v[154:157], v[204:207], v[102:105]
	v_mfma_f32_16x16x32_bf16 v[82:85], v[130:133], v[212:215], v[82:85]
	v_mfma_f32_16x16x32_bf16 v[74:77], v[154:157], v[212:215], v[74:77]
	v_mfma_f32_16x16x32_bf16 v[126:129], v[134:137], v[188:191], v[126:129]
	v_mfma_f32_16x16x32_bf16 v[122:125], v[158:161], v[188:191], v[122:125]
	v_mfma_f32_16x16x32_bf16 v[118:121], v[134:137], v[200:203], v[118:121]
	v_mfma_f32_16x16x32_bf16 v[114:117], v[158:161], v[200:203], v[114:117]
	v_mfma_f32_16x16x32_bf16 v[110:113], v[134:137], v[208:211], v[110:113]
	v_mfma_f32_16x16x32_bf16 v[102:105], v[158:161], v[208:211], v[102:105]
	v_mfma_f32_16x16x32_bf16 v[82:85], v[134:137], v[216:219], v[82:85]
	v_mfma_f32_16x16x32_bf16 v[74:77], v[158:161], v[216:219], v[74:77]
	v_mfma_f32_16x16x32_bf16 v[106:109], v[168:171], v[184:187], v[106:109]
	v_mfma_f32_16x16x32_bf16 v[98:101], v[176:179], v[184:187], v[98:101]
	v_mfma_f32_16x16x32_bf16 v[94:97], v[168:171], v[192:195], v[94:97]
	v_mfma_f32_16x16x32_bf16 v[90:93], v[176:179], v[192:195], v[90:93]
	v_mfma_f32_16x16x32_bf16 v[86:89], v[168:171], v[204:207], v[86:89]
	v_mfma_f32_16x16x32_bf16 v[78:81], v[176:179], v[204:207], v[78:81]
	v_mfma_f32_16x16x32_bf16 v[70:73], v[168:171], v[212:215], v[70:73]
	v_mfma_f32_16x16x32_bf16 v[66:69], v[176:179], v[212:215], v[66:69]
	v_mfma_f32_16x16x32_bf16 v[106:109], v[172:175], v[188:191], v[106:109]
	v_mfma_f32_16x16x32_bf16 v[98:101], v[180:183], v[188:191], v[98:101]
	v_mfma_f32_16x16x32_bf16 v[94:97], v[172:175], v[200:203], v[94:97]
	v_mfma_f32_16x16x32_bf16 v[90:93], v[180:183], v[200:203], v[90:93]
	v_mfma_f32_16x16x32_bf16 v[86:89], v[172:175], v[208:211], v[86:89]
	v_mfma_f32_16x16x32_bf16 v[78:81], v[180:183], v[208:211], v[78:81]
	v_mfma_f32_16x16x32_bf16 v[70:73], v[172:175], v[216:219], v[70:73]
	v_mfma_f32_16x16x32_bf16 v[66:69], v[180:183], v[216:219], v[66:69]
	s_barrier
	s_add_i32 s52, s44, s36
	v_lshl_add_u64 v[196:197], s[30:31], 0, v[140:141]
	s_mov_b32 m0, s52
	ds_read_b128 v[184:187], v166 offset:16384
	ds_read_b128 v[188:191], v166 offset:17408
	ds_read_b128 v[192:195], v166 offset:18432
	ds_read_b128 v[200:203], v166 offset:19456
	ds_read_b128 v[204:207], v166 offset:20480
	ds_read_b128 v[208:211], v166 offset:21504
	ds_read_b128 v[212:215], v166 offset:22528
	ds_read_b128 v[216:219], v166 offset:23552
	global_load_lds_dwordx4 v[196:197], off
	s_add_i32 m0, s52, 0x2000
	s_add_u32 s52, s30, 0x100000
	v_lshl_add_u64 v[220:221], s[30:31], 0, v[144:145]
	s_addc_u32 s53, s31, 0
	s_add_i32 s54, s45, s36
	global_load_lds_dwordx4 v[220:221], off
	v_lshl_add_u64 v[222:223], s[52:53], 0, v[140:141]
	s_mov_b32 m0, s54
	v_lshl_add_u64 v[224:225], s[34:35], 0, v[142:143]
	global_load_lds_dwordx4 v[222:223], off
	v_lshl_add_u64 v[222:223], s[52:53], 0, v[144:145]
	s_add_i32 m0, s54, 0x2000
	s_nop 0
	global_load_lds_dwordx4 v[222:223], off
	v_lshl_add_u64 v[222:223], s[34:35], 0, v[138:139]
	s_waitcnt vmcnt(6)
	s_waitcnt lgkmcnt(0)
	s_barrier
; #define PG8_STAGE(bufoff, gbase, voff) do { _Pragma("unroll") for (int _i = 0; _i < 2; ++_i) \
;         __builtin_amdgcn_global_load_lds((const unsigned*)((const char*)(gbase) + (voff)[_i]), (PG8_LAS unsigned*)(lds + (bufoff) + ldsw + _i * 8192), 16, 0, 0); } while (0)
; #define PG8_LDA(dst, b, h) do { _Pragma("unroll") for (int m = 0; m < 4; ++m) _Pragma("unroll") for (int k = 0; k < 2; ++k) dst[m][k] = *(const PG8_LAS bf16x8*)(lds + PG8_SA(b, h) + aoff + m * 2048 + k * 1024); } while (0)
; #define PG8_LDB(dst, b, h) do { _Pragma("unroll") for (int n = 0; n < 2; ++n) _Pragma("unroll") for (int k = 0; k < 2; ++k) dst[n][k] = *(const PG8_LAS bf16x8*)(lds + PG8_SB(b, h) + boff + n * 2048 + k * 1024); } while (0)
; #define PG8_MMA(ai, bj, At, Bt) do { __builtin_amdgcn_s_setprio(1); _Pragma("unroll") for (int m = 0; m < 4; ++m) _Pragma("unroll") for (int n = 0; n < 2; ++n) _Pragma("unroll") for (int k = 0; k < 2; ++k) \
;         acc[ai][bj][m][n] = __builtin_amdgcn_mfma_f32_16x16x32_bf16(Bt[n][k], At[m][k], acc[ai][bj][m][n], 0, 0, 0); __builtin_amdgcn_s_setprio(0); } while (0)
; #define PG8_WAIT_V(n) asm volatile("s_waitcnt vmcnt(" #n ")" ::: "memory")
; #define PG8_WAIT_L(n) asm volatile("s_waitcnt lgkmcnt(" #n ")" ::: "memory")
; #define PG8_BAR __builtin_amdgcn_s_barrier()
; #define PG8_SCHED __builtin_amdgcn_sched_barrier(0)
; template <class Epi, class Sched, bool ALIGN_EPI = false, bool SP2 = false>
; __device__ __forceinline__ void gemm_phase(PG8_LAS unsigned char* lds, const Gemm g, const Sched& S, const Epi& E) {
;     ...
;             PG8_WAIT_V(8); PG8_WAIT_L(0); PG8_BAR; PG8_MMA(1, 0, At, B0); PG8_MMA(1, 1, At, B1); PG8_BAR; PG8_SCHED;
;             PG8_LDB(B0, 1, 0); PG8_LDB(B1, 1, 1); PG8_SCHED; PG8_LDA(At, 1, 0); PG8_STAGE(PG8_SA(0, 1), a2 + hstep, voffA);
;             PG8_WAIT_V(8); PG8_WAIT_L(0); PG8_BAR; PG8_MMA(0, 0, At, B0); PG8_MMA(0, 1, At, B1); PG8_BAR; PG8_SCHED;
	v_mfma_f32_16x16x32_bf16 v[62:65], v[130:133], v[184:187], v[62:65]
	v_mfma_f32_16x16x32_bf16 v[58:61], v[154:157], v[184:187], v[58:61]
	v_mfma_f32_16x16x32_bf16 v[50:53], v[130:133], v[192:195], v[50:53]
	v_mfma_f32_16x16x32_bf16 v[42:45], v[154:157], v[192:195], v[42:45]
	v_mfma_f32_16x16x32_bf16 v[34:37], v[130:133], v[204:207], v[34:37]
	v_mfma_f32_16x16x32_bf16 v[26:29], v[154:157], v[204:207], v[26:29]
	v_mfma_f32_16x16x32_bf16 v[18:21], v[130:133], v[212:215], v[18:21]
	v_mfma_f32_16x16x32_bf16 v[10:13], v[154:157], v[212:215], v[10:13]
	v_mfma_f32_16x16x32_bf16 v[62:65], v[134:137], v[188:191], v[62:65]
	v_mfma_f32_16x16x32_bf16 v[58:61], v[158:161], v[188:191], v[58:61]
	v_mfma_f32_16x16x32_bf16 v[50:53], v[134:137], v[200:203], v[50:53]
	v_mfma_f32_16x16x32_bf16 v[42:45], v[158:161], v[200:203], v[42:45]
	v_mfma_f32_16x16x32_bf16 v[34:37], v[134:137], v[208:211], v[34:37]
	v_mfma_f32_16x16x32_bf16 v[26:29], v[158:161], v[208:211], v[26:29]
	v_mfma_f32_16x16x32_bf16 v[18:21], v[134:137], v[216:219], v[18:21]
	v_mfma_f32_16x16x32_bf16 v[10:13], v[158:161], v[216:219], v[10:13]
	v_mfma_f32_16x16x32_bf16 v[54:57], v[168:171], v[184:187], v[54:57]
	v_mfma_f32_16x16x32_bf16 v[46:49], v[176:179], v[184:187], v[46:49]
	v_mfma_f32_16x16x32_bf16 v[38:41], v[168:171], v[192:195], v[38:41]
	v_mfma_f32_16x16x32_bf16 v[30:33], v[176:179], v[192:195], v[30:33]
	v_mfma_f32_16x16x32_bf16 v[22:25], v[168:171], v[204:207], v[22:25]
	v_mfma_f32_16x16x32_bf16 v[14:17], v[176:179], v[204:207], v[14:17]
	v_mfma_f32_16x16x32_bf16 v[6:9], v[168:171], v[212:215], v[6:9]
	v_mfma_f32_16x16x32_bf16 v[2:5], v[176:179], v[212:215], v[2:5]
	v_mfma_f32_16x16x32_bf16 v[54:57], v[172:175], v[188:191], v[54:57]
	v_mfma_f32_16x16x32_bf16 v[46:49], v[180:183], v[188:191], v[46:49]
	v_mfma_f32_16x16x32_bf16 v[38:41], v[172:175], v[200:203], v[38:41]
	v_mfma_f32_16x16x32_bf16 v[30:33], v[180:183], v[200:203], v[30:33]
	v_mfma_f32_16x16x32_bf16 v[22:25], v[172:175], v[208:211], v[22:25]
	v_mfma_f32_16x16x32_bf16 v[14:17], v[180:183], v[208:211], v[14:17]
	v_mfma_f32_16x16x32_bf16 v[6:9], v[172:175], v[216:219], v[6:9]
	v_mfma_f32_16x16x32_bf16 v[2:5], v[180:183], v[216:219], v[2:5]
	s_barrier
	s_mov_b32 m0, s27
	s_nop 0
	global_load_lds_dwordx4 v[222:223], off
	s_mov_b32 m0, s37
	s_nop 0
	global_load_lds_dwordx4 v[224:225], off
	s_add_i32 s52, 0, 0x18000
	s_add_i32 s53, 0, 0x1c000
	v_add_u32_e32 v158, s52, v162
	v_add_u32_e32 v167, s53, v162
	ds_read_b128 v[130:133], v158
	ds_read_b128 v[134:137], v158 offset:1024
	ds_read_b128 v[154:157], v158 offset:2048
	ds_read_b128 v[158:161], v158 offset:3072
	ds_read_b128 v[168:171], v167
	ds_read_b128 v[172:175], v167 offset:1024
	ds_read_b128 v[176:179], v167 offset:2048
	ds_read_b128 v[180:183], v167 offset:3072
	s_add_u32 s34, s34, 0x100000
	s_addc_u32 s35, s35, 0
	s_mov_b32 m0, s38
	v_lshl_add_u64 v[226:227], s[34:35], 0, v[138:139]
	ds_read_b128 v[184:187], v166 offset:32768
	ds_read_b128 v[188:191], v166 offset:33792
	ds_read_b128 v[192:195], v166 offset:34816
	ds_read_b128 v[200:203], v166 offset:35840
	ds_read_b128 v[204:207], v166 offset:36864
	ds_read_b128 v[208:211], v166 offset:37888
	ds_read_b128 v[212:215], v166 offset:38912
	ds_read_b128 v[216:219], v166 offset:39936
	global_load_lds_dwordx4 v[226:227], off
	v_lshl_add_u64 v[226:227], s[34:35], 0, v[142:143]
	s_mov_b32 m0, s39
	s_nop 0
	global_load_lds_dwordx4 v[226:227], off
	s_waitcnt vmcnt(8)
	s_waitcnt lgkmcnt(0)
	s_barrier
; #define PG8_STAGE(bufoff, gbase, voff) do { _Pragma("unroll") for (int _i = 0; _i < 2; ++_i) \
;         __builtin_amdgcn_global_load_lds((const unsigned*)((const char*)(gbase) + (voff)[_i]), (PG8_LAS unsigned*)(lds + (bufoff) + ldsw + _i * 8192), 16, 0, 0); } while (0)
; #define PG8_LDA(dst, b, h) do { _Pragma("unroll") for (int m = 0; m < 4; ++m) _Pragma("unroll") for (int k = 0; k < 2; ++k) dst[m][k] = *(const PG8_LAS bf16x8*)(lds + PG8_SA(b, h) + aoff + m * 2048 + k * 1024); } while (0)
; #define PG8_MMA(ai, bj, At, Bt) do { __builtin_amdgcn_s_setprio(1); _Pragma("unroll") for (int m = 0; m < 4; ++m) _Pragma("unroll") for (int n = 0; n < 2; ++n) _Pragma("unroll") for (int k = 0; k < 2; ++k) \
;         acc[ai][bj][m][n] = __builtin_amdgcn_mfma_f32_16x16x32_bf16(Bt[n][k], At[m][k], acc[ai][bj][m][n], 0, 0, 0); __builtin_amdgcn_s_setprio(0); } while (0)
; #define PG8_WAIT_V(n) asm volatile("s_waitcnt vmcnt(" #n ")" ::: "memory")
; #define PG8_WAIT_L(n) asm volatile("s_waitcnt lgkmcnt(" #n ")" ::: "memory")
; #define PG8_BAR __builtin_amdgcn_s_barrier()
; #define PG8_SCHED __builtin_amdgcn_sched_barrier(0)
; template <class Epi, class Sched, bool ALIGN_EPI = false, bool SP2 = false>
; __device__ __forceinline__ void gemm_phase(PG8_LAS unsigned char* lds, const Gemm g, const Sched& S, const Epi& E) {
;     ...
;             PG8_WAIT_V(8); PG8_WAIT_L(0); PG8_BAR; PG8_MMA(0, 0, At, B0); PG8_MMA(0, 1, At, B1); PG8_BAR; PG8_SCHED;
;             PG8_LDA(At, 1, 1); PG8_STAGE(PG8_SB(1, 0), b3, voffB); PG8_STAGE(PG8_SB(1, 1), b3 + hstep, voffB); PG8_STAGE(PG8_SA(1, 0), a3, voffA);
;             PG8_WAIT_V(8); PG8_WAIT_L(0); PG8_BAR; PG8_MMA(1, 0, At, B0); PG8_MMA(1, 1, At, B1); PG8_BAR; PG8_SCHED;
	v_mfma_f32_16x16x32_bf16 v[126:129], v[130:133], v[184:187], v[126:129]
	v_mfma_f32_16x16x32_bf16 v[122:125], v[154:157], v[184:187], v[122:125]
	v_mfma_f32_16x16x32_bf16 v[118:121], v[130:133], v[192:195], v[118:121]
	v_mfma_f32_16x16x32_bf16 v[114:117], v[154:157], v[192:195], v[114:117]
	v_mfma_f32_16x16x32_bf16 v[110:113], v[130:133], v[204:207], v[110:113]
	v_mfma_f32_16x16x32_bf16 v[102:105], v[154:157], v[204:207], v[102:105]
	v_mfma_f32_16x16x32_bf16 v[82:85], v[130:133], v[212:215], v[82:85]
	v_mfma_f32_16x16x32_bf16 v[74:77], v[154:157], v[212:215], v[74:77]
	v_mfma_f32_16x16x32_bf16 v[126:129], v[134:137], v[188:191], v[126:129]
	v_mfma_f32_16x16x32_bf16 v[122:125], v[158:161], v[188:191], v[122:125]
	v_mfma_f32_16x16x32_bf16 v[118:121], v[134:137], v[200:203], v[118:121]
	v_mfma_f32_16x16x32_bf16 v[114:117], v[158:161], v[200:203], v[114:117]
	v_mfma_f32_16x16x32_bf16 v[110:113], v[134:137], v[208:211], v[110:113]
	v_mfma_f32_16x16x32_bf16 v[102:105], v[158:161], v[208:211], v[102:105]
	v_mfma_f32_16x16x32_bf16 v[82:85], v[134:137], v[216:219], v[82:85]
	v_mfma_f32_16x16x32_bf16 v[74:77], v[158:161], v[216:219], v[74:77]
	v_mfma_f32_16x16x32_bf16 v[106:109], v[168:171], v[184:187], v[106:109]
	v_mfma_f32_16x16x32_bf16 v[98:101], v[176:179], v[184:187], v[98:101]
	v_mfma_f32_16x16x32_bf16 v[94:97], v[168:171], v[192:195], v[94:97]
	v_mfma_f32_16x16x32_bf16 v[90:93], v[176:179], v[192:195], v[90:93]
	v_mfma_f32_16x16x32_bf16 v[86:89], v[168:171], v[204:207], v[86:89]
	v_mfma_f32_16x16x32_bf16 v[78:81], v[176:179], v[204:207], v[78:81]
	v_mfma_f32_16x16x32_bf16 v[70:73], v[168:171], v[212:215], v[70:73]
	v_mfma_f32_16x16x32_bf16 v[66:69], v[176:179], v[212:215], v[66:69]
	v_mfma_f32_16x16x32_bf16 v[106:109], v[172:175], v[188:191], v[106:109]
	v_mfma_f32_16x16x32_bf16 v[98:101], v[180:183], v[188:191], v[98:101]
	v_mfma_f32_16x16x32_bf16 v[94:97], v[172:175], v[200:203], v[94:97]
	v_mfma_f32_16x16x32_bf16 v[90:93], v[180:183], v[200:203], v[90:93]
	v_mfma_f32_16x16x32_bf16 v[86:89], v[172:175], v[208:211], v[86:89]
	v_mfma_f32_16x16x32_bf16 v[78:81], v[180:183], v[208:211], v[78:81]
	v_mfma_f32_16x16x32_bf16 v[70:73], v[172:175], v[216:219], v[70:73]
	v_mfma_f32_16x16x32_bf16 v[66:69], v[180:183], v[216:219], v[66:69]
	s_barrier
	s_add_i32 s34, s52, s36
	v_lshl_add_u64 v[196:197], v[196:197], 0, s[6:7]
	s_mov_b32 m0, s34
	ds_read_b128 v[184:187], v166 offset:49152
	ds_read_b128 v[188:191], v166 offset:50176
	ds_read_b128 v[192:195], v166 offset:51200
	ds_read_b128 v[200:203], v166 offset:52224
	ds_read_b128 v[204:207], v166 offset:53248
	ds_read_b128 v[208:211], v166 offset:54272
	ds_read_b128 v[212:215], v166 offset:55296
	ds_read_b128 v[216:219], v166 offset:56320
	global_load_lds_dwordx4 v[196:197], off
	s_add_i32 m0, s34, 0x2000
	s_add_u32 s30, s30, 0x100080
	v_lshl_add_u64 v[196:197], v[220:221], 0, s[6:7]
	s_addc_u32 s31, s31, 0
	s_add_i32 s34, s53, s36
	global_load_lds_dwordx4 v[196:197], off
	v_lshl_add_u64 v[196:197], s[30:31], 0, v[140:141]
	s_mov_b32 m0, s34
	s_nop 0
	global_load_lds_dwordx4 v[196:197], off
	v_lshl_add_u64 v[196:197], s[30:31], 0, v[144:145]
	s_add_i32 m0, s34, 0x2000
	s_nop 0
	global_load_lds_dwordx4 v[196:197], off
	s_waitcnt vmcnt(6)
	s_waitcnt lgkmcnt(0)
	s_barrier
	v_mfma_f32_16x16x32_bf16 v[62:65], v[130:133], v[184:187], v[62:65]
	v_mfma_f32_16x16x32_bf16 v[58:61], v[154:157], v[184:187], v[58:61]
	v_mfma_f32_16x16x32_bf16 v[50:53], v[130:133], v[192:195], v[50:53]
	v_mfma_f32_16x16x32_bf16 v[42:45], v[154:157], v[192:195], v[42:45]
	v_mfma_f32_16x16x32_bf16 v[34:37], v[130:133], v[204:207], v[34:37]
	v_mfma_f32_16x16x32_bf16 v[26:29], v[154:157], v[204:207], v[26:29]
	v_mfma_f32_16x16x32_bf16 v[18:21], v[130:133], v[212:215], v[18:21]
	v_mfma_f32_16x16x32_bf16 v[10:13], v[154:157], v[212:215], v[10:13]
	v_mfma_f32_16x16x32_bf16 v[62:65], v[134:137], v[188:191], v[62:65]
	v_mfma_f32_16x16x32_bf16 v[58:61], v[158:161], v[188:191], v[58:61]
	v_mfma_f32_16x16x32_bf16 v[50:53], v[134:137], v[200:203], v[50:53]
	v_mfma_f32_16x16x32_bf16 v[42:45], v[158:161], v[200:203], v[42:45]
	v_mfma_f32_16x16x32_bf16 v[34:37], v[134:137], v[208:211], v[34:37]
	v_mfma_f32_16x16x32_bf16 v[26:29], v[158:161], v[208:211], v[26:29]
	v_mfma_f32_16x16x32_bf16 v[18:21], v[134:137], v[216:219], v[18:21]
	v_mfma_f32_16x16x32_bf16 v[10:13], v[158:161], v[216:219], v[10:13]
	v_mfma_f32_16x16x32_bf16 v[54:57], v[168:171], v[184:187], v[54:57]
	v_mfma_f32_16x16x32_bf16 v[46:49], v[176:179], v[184:187], v[46:49]
	v_mfma_f32_16x16x32_bf16 v[38:41], v[168:171], v[192:195], v[38:41]
	v_mfma_f32_16x16x32_bf16 v[30:33], v[176:179], v[192:195], v[30:33]
	v_mfma_f32_16x16x32_bf16 v[22:25], v[168:171], v[204:207], v[22:25]
	v_mfma_f32_16x16x32_bf16 v[14:17], v[176:179], v[204:207], v[14:17]
	v_mfma_f32_16x16x32_bf16 v[6:9], v[168:171], v[212:215], v[6:9]
	v_mfma_f32_16x16x32_bf16 v[2:5], v[176:179], v[212:215], v[2:5]
	v_mfma_f32_16x16x32_bf16 v[54:57], v[172:175], v[188:191], v[54:57]
	v_mfma_f32_16x16x32_bf16 v[46:49], v[180:183], v[188:191], v[46:49]
	v_mfma_f32_16x16x32_bf16 v[38:41], v[172:175], v[200:203], v[38:41]
	v_mfma_f32_16x16x32_bf16 v[30:33], v[180:183], v[200:203], v[30:33]
	v_mfma_f32_16x16x32_bf16 v[22:25], v[172:175], v[208:211], v[22:25]
	v_mfma_f32_16x16x32_bf16 v[14:17], v[180:183], v[208:211], v[14:17]
	v_mfma_f32_16x16x32_bf16 v[6:9], v[172:175], v[216:219], v[6:9]
	v_mfma_f32_16x16x32_bf16 v[2:5], v[180:183], v[216:219], v[2:5]
	s_barrier
	s_add_i32 s51, s51, 2
	s_add_u32 s28, s28, 0x100
	s_addc_u32 s29, s29, 0
	s_add_u32 s49, s49, 0x100
	s_addc_u32 s50, s50, 0
	s_cmp_gt_u32 s51, 61
	s_cbranch_scc0 .LBB0_959
	s_and_b64 vcc, exec, s[8:9]
	s_cbranch_vccz .LBB0_962
	s_barrier

; #define PG8_STAGE(bufoff, gbase, voff) do { _Pragma("unroll") for (int _i = 0; _i < 2; ++_i) \
;         __builtin_amdgcn_global_load_lds((const unsigned*)((const char*)(gbase) + (voff)[_i]), (PG8_LAS unsigned*)(lds + (bufoff) + ldsw + _i * 8192), 16, 0, 0); } while (0)
; #define PG8_LDA(dst, b, h) do { _Pragma("unroll") for (int m = 0; m < 4; ++m) _Pragma("unroll") for (int k = 0; k < 2; ++k) dst[m][k] = *(const PG8_LAS bf16x8*)(lds + PG8_SA(b, h) + aoff + m * 2048 + k * 1024); } while (0)
; #define PG8_LDB(dst, b, h) do { _Pragma("unroll") for (int n = 0; n < 2; ++n) _Pragma("unroll") for (int k = 0; k < 2; ++k) dst[n][k] = *(const PG8_LAS bf16x8*)(lds + PG8_SB(b, h) + boff + n * 2048 + k * 1024); } while (0)
; #define PG8_MMA(ai, bj, At, Bt) do { __builtin_amdgcn_s_setprio(1); _Pragma("unroll") for (int m = 0; m < 4; ++m) _Pragma("unroll") for (int n = 0; n < 2; ++n) _Pragma("unroll") for (int k = 0; k < 2; ++k) \
;         acc[ai][bj][m][n] = __builtin_amdgcn_mfma_f32_16x16x32_bf16(Bt[n][k], At[m][k], acc[ai][bj][m][n], 0, 0, 0); __builtin_amdgcn_s_setprio(0); } while (0)
; #define PG8_WAIT_V(n) asm volatile("s_waitcnt vmcnt(" #n ")" ::: "memory")
; #define PG8_WAIT_L(n) asm volatile("s_waitcnt lgkmcnt(" #n ")" ::: "memory")
; template <class Epi, class Sched, bool ALIGN_EPI = false, bool SP2 = false>
; __device__ __forceinline__ void gemm_phase(PG8_LAS unsigned char* lds, const Gemm g, const Sched& S, const Epi& E) {
;     ...
;             const bool last = (t == nt - 2);
;             const char* a1 = cA + (size_t)(t + 1) * kstep;
;             const char* a2 = last ? nA : cA + (size_t)(t + 2) * kstep; const char* b2 = last ? nB : cB + (size_t)(t + 2) * kstep;
;             const char* a3 = a2 + kstep; const char* b3 = b2 + kstep;
;             if (last && has_next) S.a_ready(nxt);
;             if constexpr (SP2) {
;             PG8_LDB(B0, 0, 0); PG8_LDB(B1, 0, 1); PG8_SCHED; PG8_LDA(At, 0, 0); PG8_STAGE(PG8_SA(1, 1), a1 + hstep, voffA);
;             PG8_WAIT_V(8); PG8_WAIT_L(0); PG8_BAR; PG8_MMA(0, 0, At, B0); PG8_MMA(0, 1, At, B1); PG8_BAR; PG8_SCHED;
;             PG8_LDA(At, 0, 1); PG8_STAGE(PG8_SB(0, 0), b2, voffB); PG8_STAGE(PG8_SB(0, 1), b2 + hstep, voffB); PG8_STAGE(PG8_SA(0, 0), a2, voffA);
;             PG8_WAIT_V(8); PG8_WAIT_L(0); PG8_BAR; PG8_MMA(1, 0, At, B0); PG8_MMA(1, 1, At, B1); PG8_BAR; PG8_SCHED;
.LBB0_1081:
	s_add_u32 s34, s30, 0xfff00000
	s_addc_u32 s35, s31, -1
	v_lshl_add_u64 v[146:147], s[34:35], 0, v[136:137]
	s_mov_b32 m0, s44
	s_nop 0
	global_load_lds_dwordx4 v[146:147], off
	v_lshl_add_u64 v[146:147], s[34:35], 0, v[132:133]
	s_mov_b32 m0, s45
	s_nop 0
	global_load_lds_dwordx4 v[146:147], off
	s_add_u32 s34, s34, 0x80
	s_addc_u32 s35, s35, 0
	ds_read_b128 v[154:157], v150
	ds_read_b128 v[158:161], v150 offset:1024
	ds_read_b128 v[162:165], v150 offset:2048
	ds_read_b128 v[166:169], v150 offset:3072
	ds_read_b128 v[170:173], v151
	ds_read_b128 v[174:177], v151 offset:1024
	ds_read_b128 v[178:181], v151 offset:2048
	ds_read_b128 v[182:185], v151 offset:3072
	s_cmp_eq_u32 s55, 60
	s_cselect_b32 s37, s15, s35
	s_cselect_b32 s36, s51, s34
	s_cselect_b32 s35, s13, s54
	s_cselect_b32 s34, s52, s53
	v_lshl_add_u64 v[146:147], s[30:31], 0, v[138:139]
	s_add_i32 m0, s29, 0xc000
	ds_read_b128 v[186:189], v152
	ds_read_b128 v[190:193], v152 offset:1024
	ds_read_b128 v[194:197], v152 offset:2048
	ds_read_b128 v[200:203], v152 offset:3072
	ds_read_b128 v[204:207], v152 offset:4096
	ds_read_b128 v[208:211], v152 offset:5120
	ds_read_b128 v[212:215], v152 offset:6144
	ds_read_b128 v[216:219], v152 offset:7168
	global_load_lds_dwordx4 v[146:147], off
	v_lshl_add_u64 v[146:147], s[30:31], 0, v[140:141]
	s_add_i32 m0, s29, 0xe000
	s_nop 0
	global_load_lds_dwordx4 v[146:147], off
	s_waitcnt vmcnt(8)
	s_waitcnt lgkmcnt(0)
	s_barrier
	v_mfma_f32_16x16x32_bf16 v[126:129], v[154:157], v[186:189], v[126:129]
	v_mfma_f32_16x16x32_bf16 v[122:125], v[162:165], v[186:189], v[122:125]
	v_mfma_f32_16x16x32_bf16 v[110:113], v[154:157], v[194:197], v[110:113]
	v_mfma_f32_16x16x32_bf16 v[106:109], v[162:165], v[194:197], v[106:109]
	v_mfma_f32_16x16x32_bf16 v[94:97], v[154:157], v[204:207], v[94:97]
	v_mfma_f32_16x16x32_bf16 v[90:93], v[162:165], v[204:207], v[90:93]
	v_mfma_f32_16x16x32_bf16 v[78:81], v[154:157], v[212:215], v[78:81]
	v_mfma_f32_16x16x32_bf16 v[74:77], v[162:165], v[212:215], v[74:77]
	v_mfma_f32_16x16x32_bf16 v[126:129], v[158:161], v[190:193], v[126:129]
	v_mfma_f32_16x16x32_bf16 v[122:125], v[166:169], v[190:193], v[122:125]
	v_mfma_f32_16x16x32_bf16 v[110:113], v[158:161], v[200:203], v[110:113]
	v_mfma_f32_16x16x32_bf16 v[106:109], v[166:169], v[200:203], v[106:109]
	v_mfma_f32_16x16x32_bf16 v[94:97], v[158:161], v[208:211], v[94:97]
	v_mfma_f32_16x16x32_bf16 v[90:93], v[166:169], v[208:211], v[90:93]
	v_mfma_f32_16x16x32_bf16 v[78:81], v[158:161], v[216:219], v[78:81]
	v_mfma_f32_16x16x32_bf16 v[74:77], v[166:169], v[216:219], v[74:77]
	v_mfma_f32_16x16x32_bf16 v[118:121], v[170:173], v[186:189], v[118:121]
	v_mfma_f32_16x16x32_bf16 v[114:117], v[178:181], v[186:189], v[114:117]
	v_mfma_f32_16x16x32_bf16 v[102:105], v[170:173], v[194:197], v[102:105]
	v_mfma_f32_16x16x32_bf16 v[98:101], v[178:181], v[194:197], v[98:101]
	v_mfma_f32_16x16x32_bf16 v[86:89], v[170:173], v[204:207], v[86:89]
	v_mfma_f32_16x16x32_bf16 v[82:85], v[178:181], v[204:207], v[82:85]
	v_mfma_f32_16x16x32_bf16 v[70:73], v[170:173], v[212:215], v[70:73]
	v_mfma_f32_16x16x32_bf16 v[66:69], v[178:181], v[212:215], v[66:69]
	v_mfma_f32_16x16x32_bf16 v[118:121], v[174:177], v[190:193], v[118:121]
	v_mfma_f32_16x16x32_bf16 v[114:117], v[182:185], v[190:193], v[114:117]
	v_mfma_f32_16x16x32_bf16 v[102:105], v[174:177], v[200:203], v[102:105]
	v_mfma_f32_16x16x32_bf16 v[98:101], v[182:185], v[200:203], v[98:101]
	v_mfma_f32_16x16x32_bf16 v[86:89], v[174:177], v[208:211], v[86:89]
	v_mfma_f32_16x16x32_bf16 v[82:85], v[182:185], v[208:211], v[82:85]
	v_mfma_f32_16x16x32_bf16 v[70:73], v[174:177], v[216:219], v[70:73]
	v_mfma_f32_16x16x32_bf16 v[66:69], v[182:185], v[216:219], v[66:69]
	s_barrier
	s_add_i32 s56, s47, s33
	v_lshl_add_u64 v[146:147], s[34:35], 0, v[134:135]
	s_mov_b32 m0, s56
	ds_read_b128 v[186:189], v152 offset:16384
	ds_read_b128 v[190:193], v152 offset:17408
	ds_read_b128 v[194:197], v152 offset:18432
	ds_read_b128 v[200:203], v152 offset:19456
	ds_read_b128 v[204:207], v152 offset:20480
	ds_read_b128 v[208:211], v152 offset:21504
	ds_read_b128 v[212:215], v152 offset:22528
	ds_read_b128 v[216:219], v152 offset:23552
	global_load_lds_dwordx4 v[146:147], off
	s_add_i32 m0, s56, 0x2000
	s_add_u32 s56, s34, 0x100000
	v_lshl_add_u64 v[220:221], s[34:35], 0, v[130:131]
	s_addc_u32 s57, s35, 0
	s_add_i32 s58, s48, s33
	global_load_lds_dwordx4 v[220:221], off
	v_lshl_add_u64 v[222:223], s[56:57], 0, v[134:135]
	s_mov_b32 m0, s58
	v_lshl_add_u64 v[224:225], s[36:37], 0, v[132:133]
	global_load_lds_dwordx4 v[222:223], off
	v_lshl_add_u64 v[222:223], s[56:57], 0, v[130:131]
	s_add_i32 m0, s58, 0x2000
	s_nop 0
	global_load_lds_dwordx4 v[222:223], off
	v_lshl_add_u64 v[222:223], s[36:37], 0, v[136:137]
	s_waitcnt vmcnt(6)
	s_waitcnt lgkmcnt(0)
	s_barrier
; #define PG8_STAGE(bufoff, gbase, voff) do { _Pragma("unroll") for (int _i = 0; _i < 2; ++_i) \
;         __builtin_amdgcn_global_load_lds((const unsigned*)((const char*)(gbase) + (voff)[_i]), (PG8_LAS unsigned*)(lds + (bufoff) + ldsw + _i * 8192), 16, 0, 0); } while (0)
; #define PG8_LDA(dst, b, h) do { _Pragma("unroll") for (int m = 0; m < 4; ++m) _Pragma("unroll") for (int k = 0; k < 2; ++k) dst[m][k] = *(const PG8_LAS bf16x8*)(lds + PG8_SA(b, h) + aoff + m * 2048 + k * 1024); } while (0)
; #define PG8_LDB(dst, b, h) do { _Pragma("unroll") for (int n = 0; n < 2; ++n) _Pragma("unroll") for (int k = 0; k < 2; ++k) dst[n][k] = *(const PG8_LAS bf16x8*)(lds + PG8_SB(b, h) + boff + n * 2048 + k * 1024); } while (0)
; #define PG8_MMA(ai, bj, At, Bt) do { __builtin_amdgcn_s_setprio(1); _Pragma("unroll") for (int m = 0; m < 4; ++m) _Pragma("unroll") for (int n = 0; n < 2; ++n) _Pragma("unroll") for (int k = 0; k < 2; ++k) \
;         acc[ai][bj][m][n] = __builtin_amdgcn_mfma_f32_16x16x32_bf16(Bt[n][k], At[m][k], acc[ai][bj][m][n], 0, 0, 0); __builtin_amdgcn_s_setprio(0); } while (0)
; #define PG8_WAIT_V(n) asm volatile("s_waitcnt vmcnt(" #n ")" ::: "memory")
; #define PG8_WAIT_L(n) asm volatile("s_waitcnt lgkmcnt(" #n ")" ::: "memory")
; #define PG8_BAR __builtin_amdgcn_s_barrier()
; #define PG8_SCHED __builtin_amdgcn_sched_barrier(0)
; template <class Epi, class Sched, bool ALIGN_EPI = false, bool SP2 = false>
; __device__ __forceinline__ void gemm_phase(PG8_LAS unsigned char* lds, const Gemm g, const Sched& S, const Epi& E) {
;     ...
;             PG8_WAIT_V(8); PG8_WAIT_L(0); PG8_BAR; PG8_MMA(1, 0, At, B0); PG8_MMA(1, 1, At, B1); PG8_BAR; PG8_SCHED;
;             PG8_LDB(B0, 1, 0); PG8_LDB(B1, 1, 1); PG8_SCHED; PG8_LDA(At, 1, 0); PG8_STAGE(PG8_SA(0, 1), a2 + hstep, voffA);
;             PG8_WAIT_V(8); PG8_WAIT_L(0); PG8_BAR; PG8_MMA(0, 0, At, B0); PG8_MMA(0, 1, At, B1); PG8_BAR; PG8_SCHED;
	v_mfma_f32_16x16x32_bf16 v[62:65], v[154:157], v[186:189], v[62:65]
	v_mfma_f32_16x16x32_bf16 v[58:61], v[162:165], v[186:189], v[58:61]
	v_mfma_f32_16x16x32_bf16 v[46:49], v[154:157], v[194:197], v[46:49]
	v_mfma_f32_16x16x32_bf16 v[42:45], v[162:165], v[194:197], v[42:45]
	v_mfma_f32_16x16x32_bf16 v[30:33], v[154:157], v[204:207], v[30:33]
	v_mfma_f32_16x16x32_bf16 v[26:29], v[162:165], v[204:207], v[26:29]
	v_mfma_f32_16x16x32_bf16 v[14:17], v[154:157], v[212:215], v[14:17]
	v_mfma_f32_16x16x32_bf16 v[10:13], v[162:165], v[212:215], v[10:13]
	v_mfma_f32_16x16x32_bf16 v[62:65], v[158:161], v[190:193], v[62:65]
	v_mfma_f32_16x16x32_bf16 v[58:61], v[166:169], v[190:193], v[58:61]
	v_mfma_f32_16x16x32_bf16 v[46:49], v[158:161], v[200:203], v[46:49]
	v_mfma_f32_16x16x32_bf16 v[42:45], v[166:169], v[200:203], v[42:45]
	v_mfma_f32_16x16x32_bf16 v[30:33], v[158:161], v[208:211], v[30:33]
	v_mfma_f32_16x16x32_bf16 v[26:29], v[166:169], v[208:211], v[26:29]
	v_mfma_f32_16x16x32_bf16 v[14:17], v[158:161], v[216:219], v[14:17]
	v_mfma_f32_16x16x32_bf16 v[10:13], v[166:169], v[216:219], v[10:13]
	v_mfma_f32_16x16x32_bf16 v[54:57], v[170:173], v[186:189], v[54:57]
	v_mfma_f32_16x16x32_bf16 v[50:53], v[178:181], v[186:189], v[50:53]
	v_mfma_f32_16x16x32_bf16 v[38:41], v[170:173], v[194:197], v[38:41]
	v_mfma_f32_16x16x32_bf16 v[34:37], v[178:181], v[194:197], v[34:37]
	v_mfma_f32_16x16x32_bf16 v[22:25], v[170:173], v[204:207], v[22:25]
	v_mfma_f32_16x16x32_bf16 v[18:21], v[178:181], v[204:207], v[18:21]
	v_mfma_f32_16x16x32_bf16 v[6:9], v[170:173], v[212:215], v[6:9]
	v_mfma_f32_16x16x32_bf16 v[2:5], v[178:181], v[212:215], v[2:5]
	v_mfma_f32_16x16x32_bf16 v[54:57], v[174:177], v[190:193], v[54:57]
	v_mfma_f32_16x16x32_bf16 v[50:53], v[182:185], v[190:193], v[50:53]
	v_mfma_f32_16x16x32_bf16 v[38:41], v[174:177], v[200:203], v[38:41]
	v_mfma_f32_16x16x32_bf16 v[34:37], v[182:185], v[200:203], v[34:37]
	v_mfma_f32_16x16x32_bf16 v[22:25], v[174:177], v[208:211], v[22:25]
	v_mfma_f32_16x16x32_bf16 v[18:21], v[182:185], v[208:211], v[18:21]
	v_mfma_f32_16x16x32_bf16 v[6:9], v[174:177], v[216:219], v[6:9]
	v_mfma_f32_16x16x32_bf16 v[2:5], v[182:185], v[216:219], v[2:5]
	s_barrier
	s_mov_b32 m0, s29
	s_nop 0
	global_load_lds_dwordx4 v[222:223], off
	s_mov_b32 m0, s40
	s_nop 0
	global_load_lds_dwordx4 v[224:225], off
	s_add_i32 s56, 0, 0x18000
	v_add_u32_e32 v153, s56, v148
	s_add_i32 s57, 0, 0x1c000
	ds_read_b128 v[154:157], v153
	ds_read_b128 v[158:161], v153 offset:1024
	ds_read_b128 v[162:165], v153 offset:2048
	ds_read_b128 v[166:169], v153 offset:3072
	v_add_u32_e32 v153, s57, v148
	ds_read_b128 v[170:173], v153
	ds_read_b128 v[174:177], v153 offset:1024
	ds_read_b128 v[178:181], v153 offset:2048
	ds_read_b128 v[182:185], v153 offset:3072
	s_add_u32 s36, s36, 0x100000
	s_addc_u32 s37, s37, 0
	s_mov_b32 m0, s41
	v_lshl_add_u64 v[226:227], s[36:37], 0, v[136:137]
	ds_read_b128 v[186:189], v152 offset:32768
	ds_read_b128 v[190:193], v152 offset:33792
	ds_read_b128 v[194:197], v152 offset:34816
	ds_read_b128 v[200:203], v152 offset:35840
	ds_read_b128 v[204:207], v152 offset:36864
	ds_read_b128 v[208:211], v152 offset:37888
	ds_read_b128 v[212:215], v152 offset:38912
	ds_read_b128 v[216:219], v152 offset:39936
	global_load_lds_dwordx4 v[226:227], off
	v_lshl_add_u64 v[226:227], s[36:37], 0, v[132:133]
	s_mov_b32 m0, s42
	s_nop 0
	global_load_lds_dwordx4 v[226:227], off
	s_waitcnt vmcnt(8)
	s_waitcnt lgkmcnt(0)
	s_barrier
; #define PG8_STAGE(bufoff, gbase, voff) do { _Pragma("unroll") for (int _i = 0; _i < 2; ++_i) \
;         __builtin_amdgcn_global_load_lds((const unsigned*)((const char*)(gbase) + (voff)[_i]), (PG8_LAS unsigned*)(lds + (bufoff) + ldsw + _i * 8192), 16, 0, 0); } while (0)
; #define PG8_LDA(dst, b, h) do { _Pragma("unroll") for (int m = 0; m < 4; ++m) _Pragma("unroll") for (int k = 0; k < 2; ++k) dst[m][k] = *(const PG8_LAS bf16x8*)(lds + PG8_SA(b, h) + aoff + m * 2048 + k * 1024); } while (0)
; #define PG8_MMA(ai, bj, At, Bt) do { __builtin_amdgcn_s_setprio(1); _Pragma("unroll") for (int m = 0; m < 4; ++m) _Pragma("unroll") for (int n = 0; n < 2; ++n) _Pragma("unroll") for (int k = 0; k < 2; ++k) \
;         acc[ai][bj][m][n] = __builtin_amdgcn_mfma_f32_16x16x32_bf16(Bt[n][k], At[m][k], acc[ai][bj][m][n], 0, 0, 0); __builtin_amdgcn_s_setprio(0); } while (0)
; #define PG8_WAIT_V(n) asm volatile("s_waitcnt vmcnt(" #n ")" ::: "memory")
; #define PG8_WAIT_L(n) asm volatile("s_waitcnt lgkmcnt(" #n ")" ::: "memory")
; #define PG8_BAR __builtin_amdgcn_s_barrier()
; #define PG8_SCHED __builtin_amdgcn_sched_barrier(0)
; template <class Epi, class Sched, bool ALIGN_EPI = false, bool SP2 = false>
; __device__ __forceinline__ void gemm_phase(PG8_LAS unsigned char* lds, const Gemm g, const Sched& S, const Epi& E) {
;     ...
;             PG8_WAIT_V(8); PG8_WAIT_L(0); PG8_BAR; PG8_MMA(0, 0, At, B0); PG8_MMA(0, 1, At, B1); PG8_BAR; PG8_SCHED;
;             PG8_LDA(At, 1, 1); PG8_STAGE(PG8_SB(1, 0), b3, voffB); PG8_STAGE(PG8_SB(1, 1), b3 + hstep, voffB); PG8_STAGE(PG8_SA(1, 0), a3, voffA);
;             PG8_WAIT_V(8); PG8_WAIT_L(0); PG8_BAR; PG8_MMA(1, 0, At, B0); PG8_MMA(1, 1, At, B1); PG8_BAR; PG8_SCHED;
	v_mfma_f32_16x16x32_bf16 v[126:129], v[154:157], v[186:189], v[126:129]
	v_mfma_f32_16x16x32_bf16 v[122:125], v[162:165], v[186:189], v[122:125]
	v_mfma_f32_16x16x32_bf16 v[110:113], v[154:157], v[194:197], v[110:113]
	v_mfma_f32_16x16x32_bf16 v[106:109], v[162:165], v[194:197], v[106:109]
	v_mfma_f32_16x16x32_bf16 v[94:97], v[154:157], v[204:207], v[94:97]
	v_mfma_f32_16x16x32_bf16 v[90:93], v[162:165], v[204:207], v[90:93]
	v_mfma_f32_16x16x32_bf16 v[78:81], v[154:157], v[212:215], v[78:81]
	v_mfma_f32_16x16x32_bf16 v[74:77], v[162:165], v[212:215], v[74:77]
	v_mfma_f32_16x16x32_bf16 v[126:129], v[158:161], v[190:193], v[126:129]
	v_mfma_f32_16x16x32_bf16 v[122:125], v[166:169], v[190:193], v[122:125]
	v_mfma_f32_16x16x32_bf16 v[110:113], v[158:161], v[200:203], v[110:113]
	v_mfma_f32_16x16x32_bf16 v[106:109], v[166:169], v[200:203], v[106:109]
	v_mfma_f32_16x16x32_bf16 v[94:97], v[158:161], v[208:211], v[94:97]
	v_mfma_f32_16x16x32_bf16 v[90:93], v[166:169], v[208:211], v[90:93]
	v_mfma_f32_16x16x32_bf16 v[78:81], v[158:161], v[216:219], v[78:81]
	v_mfma_f32_16x16x32_bf16 v[74:77], v[166:169], v[216:219], v[74:77]
	v_mfma_f32_16x16x32_bf16 v[118:121], v[170:173], v[186:189], v[118:121]
	v_mfma_f32_16x16x32_bf16 v[114:117], v[178:181], v[186:189], v[114:117]
	v_mfma_f32_16x16x32_bf16 v[102:105], v[170:173], v[194:197], v[102:105]
	v_mfma_f32_16x16x32_bf16 v[98:101], v[178:181], v[194:197], v[98:101]
	v_mfma_f32_16x16x32_bf16 v[86:89], v[170:173], v[204:207], v[86:89]
	v_mfma_f32_16x16x32_bf16 v[82:85], v[178:181], v[204:207], v[82:85]
	v_mfma_f32_16x16x32_bf16 v[70:73], v[170:173], v[212:215], v[70:73]
	v_mfma_f32_16x16x32_bf16 v[66:69], v[178:181], v[212:215], v[66:69]
	v_mfma_f32_16x16x32_bf16 v[118:121], v[174:177], v[190:193], v[118:121]
	v_mfma_f32_16x16x32_bf16 v[114:117], v[182:185], v[190:193], v[114:117]
	v_mfma_f32_16x16x32_bf16 v[102:105], v[174:177], v[200:203], v[102:105]
	v_mfma_f32_16x16x32_bf16 v[98:101], v[182:185], v[200:203], v[98:101]
	v_mfma_f32_16x16x32_bf16 v[86:89], v[174:177], v[208:211], v[86:89]
	v_mfma_f32_16x16x32_bf16 v[82:85], v[182:185], v[208:211], v[82:85]
	v_mfma_f32_16x16x32_bf16 v[70:73], v[174:177], v[216:219], v[70:73]
	v_mfma_f32_16x16x32_bf16 v[66:69], v[182:185], v[216:219], v[66:69]
	s_barrier
	s_add_i32 s36, s56, s33
	v_lshl_add_u64 v[146:147], v[146:147], 0, s[8:9]
	s_mov_b32 m0, s36
	ds_read_b128 v[186:189], v152 offset:49152
	ds_read_b128 v[190:193], v152 offset:50176
	ds_read_b128 v[194:197], v152 offset:51200
	ds_read_b128 v[200:203], v152 offset:52224
	ds_read_b128 v[204:207], v152 offset:53248
	ds_read_b128 v[208:211], v152 offset:54272
	ds_read_b128 v[212:215], v152 offset:55296
	ds_read_b128 v[216:219], v152 offset:56320
	global_load_lds_dwordx4 v[146:147], off
	s_add_i32 m0, s36, 0x2000
	s_add_u32 s34, s34, 0x100080
	v_lshl_add_u64 v[146:147], v[220:221], 0, s[8:9]
	s_addc_u32 s35, s35, 0
	s_add_i32 s36, s57, s33
	global_load_lds_dwordx4 v[146:147], off
	v_lshl_add_u64 v[146:147], s[34:35], 0, v[134:135]
	s_mov_b32 m0, s36
	s_nop 0
	global_load_lds_dwordx4 v[146:147], off
	v_lshl_add_u64 v[146:147], s[34:35], 0, v[130:131]
	s_add_i32 m0, s36, 0x2000
	s_nop 0
	global_load_lds_dwordx4 v[146:147], off
	s_waitcnt vmcnt(6)
	s_waitcnt lgkmcnt(0)
	s_barrier
	v_mfma_f32_16x16x32_bf16 v[62:65], v[154:157], v[186:189], v[62:65]
	v_mfma_f32_16x16x32_bf16 v[58:61], v[162:165], v[186:189], v[58:61]
	v_mfma_f32_16x16x32_bf16 v[46:49], v[154:157], v[194:197], v[46:49]
	v_mfma_f32_16x16x32_bf16 v[42:45], v[162:165], v[194:197], v[42:45]
	v_mfma_f32_16x16x32_bf16 v[30:33], v[154:157], v[204:207], v[30:33]
	v_mfma_f32_16x16x32_bf16 v[26:29], v[162:165], v[204:207], v[26:29]
	v_mfma_f32_16x16x32_bf16 v[14:17], v[154:157], v[212:215], v[14:17]
	v_mfma_f32_16x16x32_bf16 v[10:13], v[162:165], v[212:215], v[10:13]
	v_mfma_f32_16x16x32_bf16 v[62:65], v[158:161], v[190:193], v[62:65]
	v_mfma_f32_16x16x32_bf16 v[58:61], v[166:169], v[190:193], v[58:61]
	v_mfma_f32_16x16x32_bf16 v[46:49], v[158:161], v[200:203], v[46:49]
	v_mfma_f32_16x16x32_bf16 v[42:45], v[166:169], v[200:203], v[42:45]
	v_mfma_f32_16x16x32_bf16 v[30:33], v[158:161], v[208:211], v[30:33]
	v_mfma_f32_16x16x32_bf16 v[26:29], v[166:169], v[208:211], v[26:29]
	v_mfma_f32_16x16x32_bf16 v[14:17], v[158:161], v[216:219], v[14:17]
	v_mfma_f32_16x16x32_bf16 v[10:13], v[166:169], v[216:219], v[10:13]
	v_mfma_f32_16x16x32_bf16 v[54:57], v[170:173], v[186:189], v[54:57]
	v_mfma_f32_16x16x32_bf16 v[50:53], v[178:181], v[186:189], v[50:53]
	v_mfma_f32_16x16x32_bf16 v[38:41], v[170:173], v[194:197], v[38:41]
	v_mfma_f32_16x16x32_bf16 v[34:37], v[178:181], v[194:197], v[34:37]
	v_mfma_f32_16x16x32_bf16 v[22:25], v[170:173], v[204:207], v[22:25]
	v_mfma_f32_16x16x32_bf16 v[18:21], v[178:181], v[204:207], v[18:21]
	v_mfma_f32_16x16x32_bf16 v[6:9], v[170:173], v[212:215], v[6:9]
	v_mfma_f32_16x16x32_bf16 v[2:5], v[178:181], v[212:215], v[2:5]
	v_mfma_f32_16x16x32_bf16 v[54:57], v[174:177], v[190:193], v[54:57]
	v_mfma_f32_16x16x32_bf16 v[50:53], v[182:185], v[190:193], v[50:53]
	v_mfma_f32_16x16x32_bf16 v[38:41], v[174:177], v[200:203], v[38:41]
	v_mfma_f32_16x16x32_bf16 v[34:37], v[182:185], v[200:203], v[34:37]
	v_mfma_f32_16x16x32_bf16 v[22:25], v[174:177], v[208:211], v[22:25]
	v_mfma_f32_16x16x32_bf16 v[18:21], v[182:185], v[208:211], v[18:21]
	v_mfma_f32_16x16x32_bf16 v[6:9], v[174:177], v[216:219], v[6:9]
	v_mfma_f32_16x16x32_bf16 v[2:5], v[182:185], v[216:219], v[2:5]
	s_barrier
	s_add_i32 s55, s55, 2
	s_add_u32 s30, s30, 0x100
	s_addc_u32 s31, s31, 0
	s_add_u32 s53, s53, 0x100
	s_addc_u32 s54, s54, 0
	s_cmp_gt_u32 s55, 61
	s_cbranch_scc0 .LBB0_1081
	s_and_b64 vcc, exec, s[10:11]
	s_cbranch_vccz .LBB0_1084
	s_barrier

; #define PG8_STAGE(bufoff, gbase, voff) do { _Pragma("unroll") for (int _i = 0; _i < 2; ++_i) \
;         __builtin_amdgcn_global_load_lds((const unsigned*)((const char*)(gbase) + (voff)[_i]), (PG8_LAS unsigned*)(lds + (bufoff) + ldsw + _i * 8192), 16, 0, 0); } while (0)
; #define PG8_LDA(dst, b, h) do { _Pragma("unroll") for (int m = 0; m < 4; ++m) _Pragma("unroll") for (int k = 0; k < 2; ++k) dst[m][k] = *(const PG8_LAS bf16x8*)(lds + PG8_SA(b, h) + aoff + m * 2048 + k * 1024); } while (0)
; #define PG8_LDB(dst, b, h) do { _Pragma("unroll") for (int n = 0; n < 2; ++n) _Pragma("unroll") for (int k = 0; k < 2; ++k) dst[n][k] = *(const PG8_LAS bf16x8*)(lds + PG8_SB(b, h) + boff + n * 2048 + k * 1024); } while (0)
; #define PG8_MMA(ai, bj, At, Bt) do { __builtin_amdgcn_s_setprio(1); _Pragma("unroll") for (int m = 0; m < 4; ++m) _Pragma("unroll") for (int n = 0; n < 2; ++n) _Pragma("unroll") for (int k = 0; k < 2; ++k) \
;         acc[ai][bj][m][n] = __builtin_amdgcn_mfma_f32_16x16x32_bf16(Bt[n][k], At[m][k], acc[ai][bj][m][n], 0, 0, 0); __builtin_amdgcn_s_setprio(0); } while (0)
; #define PG8_WAIT_V(n) asm volatile("s_waitcnt vmcnt(" #n ")" ::: "memory")
; #define PG8_WAIT_L(n) asm volatile("s_waitcnt lgkmcnt(" #n ")" ::: "memory")
; template <class Epi, class Sched, bool ALIGN_EPI = false, bool SP2 = false>
; __device__ __forceinline__ void gemm_phase(PG8_LAS unsigned char* lds, const Gemm g, const Sched& S, const Epi& E) {
;     ...
;             const bool last = (t == nt - 2);
;             const char* a1 = cA + (size_t)(t + 1) * kstep;
;             const char* a2 = last ? nA : cA + (size_t)(t + 2) * kstep; const char* b2 = last ? nB : cB + (size_t)(t + 2) * kstep;
;             const char* a3 = a2 + kstep; const char* b3 = b2 + kstep;
;             if (last && has_next) S.a_ready(nxt);
;             if constexpr (SP2) {
;             PG8_LDB(B0, 0, 0); PG8_LDB(B1, 0, 1); PG8_SCHED; PG8_LDA(At, 0, 0); PG8_STAGE(PG8_SA(1, 1), a1 + hstep, voffA);
;             PG8_WAIT_V(8); PG8_WAIT_L(0); PG8_BAR; PG8_MMA(0, 0, At, B0); PG8_MMA(0, 1, At, B1); PG8_BAR; PG8_SCHED;
;             PG8_LDA(At, 0, 1); PG8_STAGE(PG8_SB(0, 0), b2, voffB); PG8_STAGE(PG8_SB(0, 1), b2 + hstep, voffB); PG8_STAGE(PG8_SA(0, 0), a2, voffA);
;             PG8_WAIT_V(8); PG8_WAIT_L(0); PG8_BAR; PG8_MMA(1, 0, At, B0); PG8_MMA(1, 1, At, B1); PG8_BAR; PG8_SCHED;
.LBB0_1164:
	s_add_u32 s16, s14, 0xffd50000
	s_addc_u32 s17, s15, -1
	v_lshl_add_u64 v[188:189], s[16:17], 0, v[128:129]
	s_mov_b32 m0, s29
	s_nop 0
	global_load_lds_dwordx4 v[188:189], off
	v_lshl_add_u64 v[188:189], s[16:17], 0, v[130:131]
	s_mov_b32 m0, s30
	s_nop 0
	global_load_lds_dwordx4 v[188:189], off
	s_add_u32 s16, s16, 0x80
	s_addc_u32 s17, s17, 0
	ds_read_b128 v[140:143], v193
	ds_read_b128 v[144:147], v193 offset:1024
	ds_read_b128 v[148:151], v193 offset:2048
	ds_read_b128 v[152:155], v193 offset:3072
	ds_read_b128 v[156:159], v194
	ds_read_b128 v[160:163], v194 offset:1024
	ds_read_b128 v[164:167], v194 offset:2048
	ds_read_b128 v[168:171], v194 offset:3072
	s_cmpk_eq_i32 s41, 0xa8
	s_cselect_b32 s21, s5, s17
	s_cselect_b32 s20, s4, s16
	s_cselect_b32 s17, s13, s40
	s_cselect_b32 s16, s12, s39
	v_lshl_add_u64 v[188:189], s[14:15], 0, v[132:133]
	s_add_i32 m0, s24, 0xc000
	ds_read_b128 v[172:175], v195
	ds_read_b128 v[176:179], v195 offset:1024
	ds_read_b128 v[180:183], v195 offset:2048
	ds_read_b128 v[184:187], v195 offset:3072
	ds_read_b128 v[196:199], v195 offset:4096
	ds_read_b128 v[200:203], v195 offset:5120
	ds_read_b128 v[204:207], v195 offset:6144
	ds_read_b128 v[208:211], v195 offset:7168
	global_load_lds_dwordx4 v[188:189], off
	v_lshl_add_u64 v[188:189], s[14:15], 0, v[134:135]
	s_add_i32 m0, s24, 0xe000
	s_nop 0
	global_load_lds_dwordx4 v[188:189], off
	s_waitcnt vmcnt(8)
	s_waitcnt lgkmcnt(0)
	s_barrier
	v_mfma_f32_16x16x32_bf16 v[124:127], v[140:143], v[172:175], v[124:127]
	v_mfma_f32_16x16x32_bf16 v[120:123], v[148:151], v[172:175], v[120:123]
	v_mfma_f32_16x16x32_bf16 v[112:115], v[140:143], v[180:183], v[112:115]
	v_mfma_f32_16x16x32_bf16 v[104:107], v[148:151], v[180:183], v[104:107]
	v_mfma_f32_16x16x32_bf16 v[96:99], v[140:143], v[196:199], v[96:99]
	v_mfma_f32_16x16x32_bf16 v[88:91], v[148:151], v[196:199], v[88:91]
	v_mfma_f32_16x16x32_bf16 v[80:83], v[140:143], v[204:207], v[80:83]
	v_mfma_f32_16x16x32_bf16 v[72:75], v[148:151], v[204:207], v[72:75]
	v_mfma_f32_16x16x32_bf16 v[124:127], v[144:147], v[176:179], v[124:127]
	v_mfma_f32_16x16x32_bf16 v[120:123], v[152:155], v[176:179], v[120:123]
	v_mfma_f32_16x16x32_bf16 v[112:115], v[144:147], v[184:187], v[112:115]
	v_mfma_f32_16x16x32_bf16 v[104:107], v[152:155], v[184:187], v[104:107]
	v_mfma_f32_16x16x32_bf16 v[96:99], v[144:147], v[200:203], v[96:99]
	v_mfma_f32_16x16x32_bf16 v[88:91], v[152:155], v[200:203], v[88:91]
	v_mfma_f32_16x16x32_bf16 v[80:83], v[144:147], v[208:211], v[80:83]
	v_mfma_f32_16x16x32_bf16 v[72:75], v[152:155], v[208:211], v[72:75]
	v_mfma_f32_16x16x32_bf16 v[116:119], v[156:159], v[172:175], v[116:119]
	v_mfma_f32_16x16x32_bf16 v[108:111], v[164:167], v[172:175], v[108:111]
	v_mfma_f32_16x16x32_bf16 v[100:103], v[156:159], v[180:183], v[100:103]
	v_mfma_f32_16x16x32_bf16 v[92:95], v[164:167], v[180:183], v[92:95]
	v_mfma_f32_16x16x32_bf16 v[84:87], v[156:159], v[196:199], v[84:87]
	v_mfma_f32_16x16x32_bf16 v[76:79], v[164:167], v[196:199], v[76:79]
	v_mfma_f32_16x16x32_bf16 v[68:71], v[156:159], v[204:207], v[68:71]
	v_mfma_f32_16x16x32_bf16 v[64:67], v[164:167], v[204:207], v[64:67]
	v_mfma_f32_16x16x32_bf16 v[116:119], v[160:163], v[176:179], v[116:119]
	v_mfma_f32_16x16x32_bf16 v[108:111], v[168:171], v[176:179], v[108:111]
	v_mfma_f32_16x16x32_bf16 v[100:103], v[160:163], v[184:187], v[100:103]
	v_mfma_f32_16x16x32_bf16 v[92:95], v[168:171], v[184:187], v[92:95]
	v_mfma_f32_16x16x32_bf16 v[84:87], v[160:163], v[200:203], v[84:87]
	v_mfma_f32_16x16x32_bf16 v[76:79], v[168:171], v[200:203], v[76:79]
	v_mfma_f32_16x16x32_bf16 v[68:71], v[160:163], v[208:211], v[68:71]
	v_mfma_f32_16x16x32_bf16 v[64:67], v[168:171], v[208:211], v[64:67]
	s_barrier
	s_add_i32 s42, s33, s23
	v_lshl_add_u64 v[188:189], s[16:17], 0, v[128:129]
	s_mov_b32 m0, s42
	ds_read_b128 v[172:175], v195 offset:16384
	ds_read_b128 v[176:179], v195 offset:17408
	ds_read_b128 v[180:183], v195 offset:18432
	ds_read_b128 v[184:187], v195 offset:19456
	ds_read_b128 v[196:199], v195 offset:20480
	ds_read_b128 v[200:203], v195 offset:21504
	ds_read_b128 v[204:207], v195 offset:22528
	ds_read_b128 v[208:211], v195 offset:23552
	global_load_lds_dwordx4 v[188:189], off
	s_add_i32 m0, s42, 0x2000
	s_add_u32 s42, s16, 0x2b0000
	v_lshl_add_u64 v[212:213], s[16:17], 0, v[130:131]
	s_addc_u32 s43, s17, 0
	s_add_i32 s44, s34, s23
	global_load_lds_dwordx4 v[212:213], off
	v_lshl_add_u64 v[214:215], s[42:43], 0, v[128:129]
	s_mov_b32 m0, s44
	v_lshl_add_u64 v[216:217], s[20:21], 0, v[130:131]
	global_load_lds_dwordx4 v[214:215], off
	v_lshl_add_u64 v[214:215], s[42:43], 0, v[130:131]
	s_add_i32 m0, s44, 0x2000
	s_nop 0
	global_load_lds_dwordx4 v[214:215], off
	v_lshl_add_u64 v[214:215], s[20:21], 0, v[128:129]
	s_waitcnt vmcnt(6)
	s_waitcnt lgkmcnt(0)
	s_barrier
; #define PG8_STAGE(bufoff, gbase, voff) do { _Pragma("unroll") for (int _i = 0; _i < 2; ++_i) \
;         __builtin_amdgcn_global_load_lds((const unsigned*)((const char*)(gbase) + (voff)[_i]), (PG8_LAS unsigned*)(lds + (bufoff) + ldsw + _i * 8192), 16, 0, 0); } while (0)
; #define PG8_LDA(dst, b, h) do { _Pragma("unroll") for (int m = 0; m < 4; ++m) _Pragma("unroll") for (int k = 0; k < 2; ++k) dst[m][k] = *(const PG8_LAS bf16x8*)(lds + PG8_SA(b, h) + aoff + m * 2048 + k * 1024); } while (0)
; #define PG8_LDB(dst, b, h) do { _Pragma("unroll") for (int n = 0; n < 2; ++n) _Pragma("unroll") for (int k = 0; k < 2; ++k) dst[n][k] = *(const PG8_LAS bf16x8*)(lds + PG8_SB(b, h) + boff + n * 2048 + k * 1024); } while (0)
; #define PG8_MMA(ai, bj, At, Bt) do { __builtin_amdgcn_s_setprio(1); _Pragma("unroll") for (int m = 0; m < 4; ++m) _Pragma("unroll") for (int n = 0; n < 2; ++n) _Pragma("unroll") for (int k = 0; k < 2; ++k) \
;         acc[ai][bj][m][n] = __builtin_amdgcn_mfma_f32_16x16x32_bf16(Bt[n][k], At[m][k], acc[ai][bj][m][n], 0, 0, 0); __builtin_amdgcn_s_setprio(0); } while (0)
; #define PG8_WAIT_V(n) asm volatile("s_waitcnt vmcnt(" #n ")" ::: "memory")
; #define PG8_WAIT_L(n) asm volatile("s_waitcnt lgkmcnt(" #n ")" ::: "memory")
; #define PG8_BAR __builtin_amdgcn_s_barrier()
; #define PG8_SCHED __builtin_amdgcn_sched_barrier(0)
; template <class Epi, class Sched, bool ALIGN_EPI = false, bool SP2 = false>
; __device__ __forceinline__ void gemm_phase(PG8_LAS unsigned char* lds, const Gemm g, const Sched& S, const Epi& E) {
;     ...
;             PG8_WAIT_V(8); PG8_WAIT_L(0); PG8_BAR; PG8_MMA(1, 0, At, B0); PG8_MMA(1, 1, At, B1); PG8_BAR; PG8_SCHED;
;             PG8_LDB(B0, 1, 0); PG8_LDB(B1, 1, 1); PG8_SCHED; PG8_LDA(At, 1, 0); PG8_STAGE(PG8_SA(0, 1), a2 + hstep, voffA);
;             PG8_WAIT_V(8); PG8_WAIT_L(0); PG8_BAR; PG8_MMA(0, 0, At, B0); PG8_MMA(0, 1, At, B1); PG8_BAR; PG8_SCHED;
	v_mfma_f32_16x16x32_bf16 v[60:63], v[140:143], v[172:175], v[60:63]
	v_mfma_f32_16x16x32_bf16 v[56:59], v[148:151], v[172:175], v[56:59]
	v_mfma_f32_16x16x32_bf16 v[48:51], v[140:143], v[180:183], v[48:51]
	v_mfma_f32_16x16x32_bf16 v[40:43], v[148:151], v[180:183], v[40:43]
	v_mfma_f32_16x16x32_bf16 v[32:35], v[140:143], v[196:199], v[32:35]
	v_mfma_f32_16x16x32_bf16 v[24:27], v[148:151], v[196:199], v[24:27]
	v_mfma_f32_16x16x32_bf16 v[16:19], v[140:143], v[204:207], v[16:19]
	v_mfma_f32_16x16x32_bf16 v[8:11], v[148:151], v[204:207], v[8:11]
	v_mfma_f32_16x16x32_bf16 v[60:63], v[144:147], v[176:179], v[60:63]
	v_mfma_f32_16x16x32_bf16 v[56:59], v[152:155], v[176:179], v[56:59]
	v_mfma_f32_16x16x32_bf16 v[48:51], v[144:147], v[184:187], v[48:51]
	v_mfma_f32_16x16x32_bf16 v[40:43], v[152:155], v[184:187], v[40:43]
	v_mfma_f32_16x16x32_bf16 v[32:35], v[144:147], v[200:203], v[32:35]
	v_mfma_f32_16x16x32_bf16 v[24:27], v[152:155], v[200:203], v[24:27]
	v_mfma_f32_16x16x32_bf16 v[16:19], v[144:147], v[208:211], v[16:19]
	v_mfma_f32_16x16x32_bf16 v[8:11], v[152:155], v[208:211], v[8:11]
	v_mfma_f32_16x16x32_bf16 v[52:55], v[156:159], v[172:175], v[52:55]
	v_mfma_f32_16x16x32_bf16 v[44:47], v[164:167], v[172:175], v[44:47]
	v_mfma_f32_16x16x32_bf16 v[36:39], v[156:159], v[180:183], v[36:39]
	v_mfma_f32_16x16x32_bf16 v[28:31], v[164:167], v[180:183], v[28:31]
	v_mfma_f32_16x16x32_bf16 v[20:23], v[156:159], v[196:199], v[20:23]
	v_mfma_f32_16x16x32_bf16 v[12:15], v[164:167], v[196:199], v[12:15]
	v_mfma_f32_16x16x32_bf16 v[4:7], v[156:159], v[204:207], v[4:7]
	v_mfma_f32_16x16x32_bf16 v[0:3], v[164:167], v[204:207], v[0:3]
	v_mfma_f32_16x16x32_bf16 v[52:55], v[160:163], v[176:179], v[52:55]
	v_mfma_f32_16x16x32_bf16 v[44:47], v[168:171], v[176:179], v[44:47]
	v_mfma_f32_16x16x32_bf16 v[36:39], v[160:163], v[184:187], v[36:39]
	v_mfma_f32_16x16x32_bf16 v[28:31], v[168:171], v[184:187], v[28:31]
	v_mfma_f32_16x16x32_bf16 v[20:23], v[160:163], v[200:203], v[20:23]
	v_mfma_f32_16x16x32_bf16 v[12:15], v[168:171], v[200:203], v[12:15]
	v_mfma_f32_16x16x32_bf16 v[4:7], v[160:163], v[208:211], v[4:7]
	v_mfma_f32_16x16x32_bf16 v[0:3], v[168:171], v[208:211], v[0:3]
	s_barrier
	s_mov_b32 m0, s24
	s_nop 0
	global_load_lds_dwordx4 v[214:215], off
	s_mov_b32 m0, s25
	s_nop 0
	global_load_lds_dwordx4 v[216:217], off
	s_add_i32 s42, 0, 0x18000
	s_add_i32 s43, 0, 0x1c000
	v_add_u32_e32 v152, s42, v191
	v_add_u32_e32 v168, s43, v191
	ds_read_b128 v[140:143], v152
	ds_read_b128 v[144:147], v152 offset:1024
	ds_read_b128 v[148:151], v152 offset:2048
	ds_read_b128 v[152:155], v152 offset:3072
	ds_read_b128 v[156:159], v168
	ds_read_b128 v[160:163], v168 offset:1024
	ds_read_b128 v[164:167], v168 offset:2048
	ds_read_b128 v[168:171], v168 offset:3072
	s_add_u32 s20, s20, 0x2b0000
	s_addc_u32 s21, s21, 0
	s_mov_b32 m0, s26
	v_lshl_add_u64 v[218:219], s[20:21], 0, v[128:129]
	ds_read_b128 v[172:175], v195 offset:32768
	ds_read_b128 v[176:179], v195 offset:33792
	ds_read_b128 v[180:183], v195 offset:34816
	ds_read_b128 v[184:187], v195 offset:35840
	ds_read_b128 v[196:199], v195 offset:36864
	ds_read_b128 v[200:203], v195 offset:37888
	ds_read_b128 v[204:207], v195 offset:38912
	ds_read_b128 v[208:211], v195 offset:39936
	global_load_lds_dwordx4 v[218:219], off
	v_lshl_add_u64 v[218:219], s[20:21], 0, v[130:131]
	s_mov_b32 m0, s27
	s_nop 0
	global_load_lds_dwordx4 v[218:219], off
	s_waitcnt vmcnt(8)
	s_waitcnt lgkmcnt(0)
	s_barrier
; #define PG8_STAGE(bufoff, gbase, voff) do { _Pragma("unroll") for (int _i = 0; _i < 2; ++_i) \
;         __builtin_amdgcn_global_load_lds((const unsigned*)((const char*)(gbase) + (voff)[_i]), (PG8_LAS unsigned*)(lds + (bufoff) + ldsw + _i * 8192), 16, 0, 0); } while (0)
; #define PG8_LDA(dst, b, h) do { _Pragma("unroll") for (int m = 0; m < 4; ++m) _Pragma("unroll") for (int k = 0; k < 2; ++k) dst[m][k] = *(const PG8_LAS bf16x8*)(lds + PG8_SA(b, h) + aoff + m * 2048 + k * 1024); } while (0)
; #define PG8_MMA(ai, bj, At, Bt) do { __builtin_amdgcn_s_setprio(1); _Pragma("unroll") for (int m = 0; m < 4; ++m) _Pragma("unroll") for (int n = 0; n < 2; ++n) _Pragma("unroll") for (int k = 0; k < 2; ++k) \
;         acc[ai][bj][m][n] = __builtin_amdgcn_mfma_f32_16x16x32_bf16(Bt[n][k], At[m][k], acc[ai][bj][m][n], 0, 0, 0); __builtin_amdgcn_s_setprio(0); } while (0)
; #define PG8_WAIT_V(n) asm volatile("s_waitcnt vmcnt(" #n ")" ::: "memory")
; #define PG8_WAIT_L(n) asm volatile("s_waitcnt lgkmcnt(" #n ")" ::: "memory")
; #define PG8_BAR __builtin_amdgcn_s_barrier()
; #define PG8_SCHED __builtin_amdgcn_sched_barrier(0)
; template <class Epi, class Sched, bool ALIGN_EPI = false, bool SP2 = false>
; __device__ __forceinline__ void gemm_phase(PG8_LAS unsigned char* lds, const Gemm g, const Sched& S, const Epi& E) {
;     ...
;             PG8_WAIT_V(8); PG8_WAIT_L(0); PG8_BAR; PG8_MMA(0, 0, At, B0); PG8_MMA(0, 1, At, B1); PG8_BAR; PG8_SCHED;
;             PG8_LDA(At, 1, 1); PG8_STAGE(PG8_SB(1, 0), b3, voffB); PG8_STAGE(PG8_SB(1, 1), b3 + hstep, voffB); PG8_STAGE(PG8_SA(1, 0), a3, voffA);
;             PG8_WAIT_V(8); PG8_WAIT_L(0); PG8_BAR; PG8_MMA(1, 0, At, B0); PG8_MMA(1, 1, At, B1); PG8_BAR; PG8_SCHED;
	v_mfma_f32_16x16x32_bf16 v[124:127], v[140:143], v[172:175], v[124:127]
	v_mfma_f32_16x16x32_bf16 v[120:123], v[148:151], v[172:175], v[120:123]
	v_mfma_f32_16x16x32_bf16 v[112:115], v[140:143], v[180:183], v[112:115]
	v_mfma_f32_16x16x32_bf16 v[104:107], v[148:151], v[180:183], v[104:107]
	v_mfma_f32_16x16x32_bf16 v[96:99], v[140:143], v[196:199], v[96:99]
	v_mfma_f32_16x16x32_bf16 v[88:91], v[148:151], v[196:199], v[88:91]
	v_mfma_f32_16x16x32_bf16 v[80:83], v[140:143], v[204:207], v[80:83]
	v_mfma_f32_16x16x32_bf16 v[72:75], v[148:151], v[204:207], v[72:75]
	v_mfma_f32_16x16x32_bf16 v[124:127], v[144:147], v[176:179], v[124:127]
	v_mfma_f32_16x16x32_bf16 v[120:123], v[152:155], v[176:179], v[120:123]
	v_mfma_f32_16x16x32_bf16 v[112:115], v[144:147], v[184:187], v[112:115]
	v_mfma_f32_16x16x32_bf16 v[104:107], v[152:155], v[184:187], v[104:107]
	v_mfma_f32_16x16x32_bf16 v[96:99], v[144:147], v[200:203], v[96:99]
	v_mfma_f32_16x16x32_bf16 v[88:91], v[152:155], v[200:203], v[88:91]
	v_mfma_f32_16x16x32_bf16 v[80:83], v[144:147], v[208:211], v[80:83]
	v_mfma_f32_16x16x32_bf16 v[72:75], v[152:155], v[208:211], v[72:75]
	v_mfma_f32_16x16x32_bf16 v[116:119], v[156:159], v[172:175], v[116:119]
	v_mfma_f32_16x16x32_bf16 v[108:111], v[164:167], v[172:175], v[108:111]
	v_mfma_f32_16x16x32_bf16 v[100:103], v[156:159], v[180:183], v[100:103]
	v_mfma_f32_16x16x32_bf16 v[92:95], v[164:167], v[180:183], v[92:95]
	v_mfma_f32_16x16x32_bf16 v[84:87], v[156:159], v[196:199], v[84:87]
	v_mfma_f32_16x16x32_bf16 v[76:79], v[164:167], v[196:199], v[76:79]
	v_mfma_f32_16x16x32_bf16 v[68:71], v[156:159], v[204:207], v[68:71]
	v_mfma_f32_16x16x32_bf16 v[64:67], v[164:167], v[204:207], v[64:67]
	v_mfma_f32_16x16x32_bf16 v[116:119], v[160:163], v[176:179], v[116:119]
	v_mfma_f32_16x16x32_bf16 v[108:111], v[168:171], v[176:179], v[108:111]
	v_mfma_f32_16x16x32_bf16 v[100:103], v[160:163], v[184:187], v[100:103]
	v_mfma_f32_16x16x32_bf16 v[92:95], v[168:171], v[184:187], v[92:95]
	v_mfma_f32_16x16x32_bf16 v[84:87], v[160:163], v[200:203], v[84:87]
	v_mfma_f32_16x16x32_bf16 v[76:79], v[168:171], v[200:203], v[76:79]
	v_mfma_f32_16x16x32_bf16 v[68:71], v[160:163], v[208:211], v[68:71]
	v_mfma_f32_16x16x32_bf16 v[64:67], v[168:171], v[208:211], v[64:67]
	s_barrier
	s_add_i32 s20, s42, s23
	v_lshl_add_u64 v[188:189], v[188:189], 0, s[8:9]
	s_mov_b32 m0, s20
	ds_read_b128 v[172:175], v195 offset:49152
	ds_read_b128 v[176:179], v195 offset:50176
	ds_read_b128 v[180:183], v195 offset:51200
	ds_read_b128 v[184:187], v195 offset:52224
	ds_read_b128 v[196:199], v195 offset:53248
	ds_read_b128 v[200:203], v195 offset:54272
	ds_read_b128 v[204:207], v195 offset:55296
	ds_read_b128 v[208:211], v195 offset:56320
	global_load_lds_dwordx4 v[188:189], off
	s_add_i32 m0, s20, 0x2000
	s_add_u32 s16, s16, 0x2b0080
	v_lshl_add_u64 v[188:189], v[212:213], 0, s[8:9]
	s_addc_u32 s17, s17, 0
	s_add_i32 s20, s43, s23
	global_load_lds_dwordx4 v[188:189], off
	v_lshl_add_u64 v[188:189], s[16:17], 0, v[128:129]
	s_mov_b32 m0, s20
	s_nop 0
	global_load_lds_dwordx4 v[188:189], off
	v_lshl_add_u64 v[188:189], s[16:17], 0, v[130:131]
	s_add_i32 m0, s20, 0x2000
	s_nop 0
	global_load_lds_dwordx4 v[188:189], off
	s_waitcnt vmcnt(6)
	s_waitcnt lgkmcnt(0)
	s_barrier
	v_mfma_f32_16x16x32_bf16 v[60:63], v[140:143], v[172:175], v[60:63]
	v_mfma_f32_16x16x32_bf16 v[56:59], v[148:151], v[172:175], v[56:59]
	v_mfma_f32_16x16x32_bf16 v[48:51], v[140:143], v[180:183], v[48:51]
	v_mfma_f32_16x16x32_bf16 v[40:43], v[148:151], v[180:183], v[40:43]
	v_mfma_f32_16x16x32_bf16 v[32:35], v[140:143], v[196:199], v[32:35]
	v_mfma_f32_16x16x32_bf16 v[24:27], v[148:151], v[196:199], v[24:27]
	v_mfma_f32_16x16x32_bf16 v[16:19], v[140:143], v[204:207], v[16:19]
	v_mfma_f32_16x16x32_bf16 v[8:11], v[148:151], v[204:207], v[8:11]
	v_mfma_f32_16x16x32_bf16 v[60:63], v[144:147], v[176:179], v[60:63]
	v_mfma_f32_16x16x32_bf16 v[56:59], v[152:155], v[176:179], v[56:59]
	v_mfma_f32_16x16x32_bf16 v[48:51], v[144:147], v[184:187], v[48:51]
	v_mfma_f32_16x16x32_bf16 v[40:43], v[152:155], v[184:187], v[40:43]
	v_mfma_f32_16x16x32_bf16 v[32:35], v[144:147], v[200:203], v[32:35]
	v_mfma_f32_16x16x32_bf16 v[24:27], v[152:155], v[200:203], v[24:27]
	v_mfma_f32_16x16x32_bf16 v[16:19], v[144:147], v[208:211], v[16:19]
	v_mfma_f32_16x16x32_bf16 v[8:11], v[152:155], v[208:211], v[8:11]
	v_mfma_f32_16x16x32_bf16 v[52:55], v[156:159], v[172:175], v[52:55]
	v_mfma_f32_16x16x32_bf16 v[44:47], v[164:167], v[172:175], v[44:47]
	v_mfma_f32_16x16x32_bf16 v[36:39], v[156:159], v[180:183], v[36:39]
	v_mfma_f32_16x16x32_bf16 v[28:31], v[164:167], v[180:183], v[28:31]
	v_mfma_f32_16x16x32_bf16 v[20:23], v[156:159], v[196:199], v[20:23]
	v_mfma_f32_16x16x32_bf16 v[12:15], v[164:167], v[196:199], v[12:15]
	v_mfma_f32_16x16x32_bf16 v[4:7], v[156:159], v[204:207], v[4:7]
	v_mfma_f32_16x16x32_bf16 v[0:3], v[164:167], v[204:207], v[0:3]
	v_mfma_f32_16x16x32_bf16 v[52:55], v[160:163], v[176:179], v[52:55]
	v_mfma_f32_16x16x32_bf16 v[44:47], v[168:171], v[176:179], v[44:47]
	v_mfma_f32_16x16x32_bf16 v[36:39], v[160:163], v[184:187], v[36:39]
	v_mfma_f32_16x16x32_bf16 v[28:31], v[168:171], v[184:187], v[28:31]
	v_mfma_f32_16x16x32_bf16 v[20:23], v[160:163], v[200:203], v[20:23]
	v_mfma_f32_16x16x32_bf16 v[12:15], v[168:171], v[200:203], v[12:15]
	v_mfma_f32_16x16x32_bf16 v[4:7], v[160:163], v[208:211], v[4:7]
	v_mfma_f32_16x16x32_bf16 v[0:3], v[168:171], v[208:211], v[0:3]
	s_barrier
	s_add_i32 s41, s41, 2
	s_add_u32 s14, s14, 0x100
	s_addc_u32 s15, s15, 0
	s_add_u32 s39, s39, 0x100
	s_addc_u32 s40, s40, 0
	s_cmpk_gt_u32 s41, 0xa9
	s_cbranch_scc0 .LBB0_1164
	s_and_b64 vcc, exec, s[10:11]
	s_cbranch_vccz .LBB0_1167
	s_barrier
